# v73 + K-loop load segments: LDS fragment reads issued first (LDS address adds use literals), address math for the DMA behind them
# baseline (speedup 1.0000x reference)
; #define PG8_STAGE(bufoff, gbase, voff) do { _Pragma("unroll") for (int _i = 0; _i < 2; ++_i) \
;         __builtin_amdgcn_global_load_lds((const unsigned*)((const char*)(gbase) + (voff)[_i]), (PG8_LAS unsigned*)(lds + (bufoff) + ldsw + _i * 8192), 16, 0, 0); } while (0)
; #define PG8_LDA(dst, b, h) do { _Pragma("unroll") for (int m = 0; m < 4; ++m) _Pragma("unroll") for (int k = 0; k < 2; ++k) dst[m][k] = *(const PG8_LAS bf16x8*)(lds + PG8_SA(b, h) + aoff + m * 2048 + k * 1024); } while (0)
; #define PG8_LDB(dst, b, h) do { _Pragma("unroll") for (int n = 0; n < 2; ++n) _Pragma("unroll") for (int k = 0; k < 2; ++k) dst[n][k] = *(const PG8_LAS bf16x8*)(lds + PG8_SB(b, h) + boff + n * 2048 + k * 1024); } while (0)
; #define PG8_MMA(ai, bj, At, Bt) do { __builtin_amdgcn_s_setprio(1); _Pragma("unroll") for (int m = 0; m < 4; ++m) _Pragma("unroll") for (int n = 0; n < 2; ++n) _Pragma("unroll") for (int k = 0; k < 2; ++k) \
;         acc[ai][bj][m][n] = __builtin_amdgcn_mfma_f32_16x16x32_bf16(Bt[n][k], At[m][k], acc[ai][bj][m][n], 0, 0, 0); __builtin_amdgcn_s_setprio(0); } while (0)
; #define PG8_WAIT_V(n) asm volatile("s_waitcnt vmcnt(" #n ")" ::: "memory")
; #define PG8_BAR __builtin_amdgcn_s_barrier()
; template <class Epi, class Sched, bool ALIGN_EPI = false, bool SP2 = false>
; __device__ __forceinline__ void gemm_phase(PG8_LAS unsigned char* lds, const Gemm g, const Sched& S, const Epi& E) {
;     ...
;         for (int t = 0; t < nt; t += 2) {
;             const bool last = (t == nt - 2);
;             const char* a1 = cA + (size_t)(t + 1) * kstep;
;             const char* a2 = last ? nA : cA + (size_t)(t + 2) * kstep; const char* b2 = last ? nB : cB + (size_t)(t + 2) * kstep;
;             const char* a3 = a2 + kstep; const char* b3 = b2 + kstep;
;             if (last && has_next) S.a_ready(nxt);
;             if constexpr (SP2) {
;             PG8_LDB(B0, 0, 0); PG8_LDB(B1, 0, 1); PG8_SCHED; PG8_LDA(At, 0, 0); PG8_STAGE(PG8_SA(1, 1), a1 + hstep, voffA);
;             PG8_WAIT_V(8); PG8_WAIT_L(0); PG8_BAR; PG8_MMA(0, 0, At, B0); PG8_MMA(0, 1, At, B1); PG8_BAR; PG8_SCHED;
;             PG8_LDA(At, 0, 1); PG8_STAGE(PG8_SB(0, 0), b2, voffB); PG8_STAGE(PG8_SB(0, 1), b2 + hstep, voffB); PG8_STAGE(PG8_SA(0, 0), a2, voffA);
;             PG8_WAIT_V(8); PG8_WAIT_L(0); PG8_BAR; PG8_MMA(1, 0, At, B0); PG8_MMA(1, 1, At, B1); PG8_BAR; PG8_SCHED;
.LBB0_100:
	ds_read_b128 v[164:167], v205
	ds_read_b128 v[182:185], v205 offset:1024
	ds_read_b128 v[186:189], v205 offset:2048
	ds_read_b128 v[190:193], v205 offset:3072
	ds_read_b128 v[208:211], v205 offset:4096
	ds_read_b128 v[212:215], v205 offset:5120
	ds_read_b128 v[216:219], v205 offset:6144
	ds_read_b128 v[220:223], v205 offset:7168
	v_add_u32_e32 v144, 0x10000, v204
	v_add_u32_e32 v160, 0x14000, v204
	ds_read_b128 v[132:135], v144
	ds_read_b128 v[136:139], v144 offset:1024
	ds_read_b128 v[140:143], v144 offset:2048
	ds_read_b128 v[144:147], v144 offset:3072
	ds_read_b128 v[148:151], v160
	ds_read_b128 v[152:155], v160 offset:1024
	ds_read_b128 v[156:159], v160 offset:2048
	ds_read_b128 v[160:163], v160 offset:3072
	s_add_u32 s28, s8, 0xfffc0080
	s_addc_u32 s29, s9, -1
	s_add_i32 s53, 0, 0x10000
	s_cmp_eq_u32 s45, 12
	s_cselect_b32 s31, s3, s29
	s_cselect_b32 s30, s7, s28
	s_cselect_b32 s29, s11, s44
	s_cselect_b32 s28, s21, s23
	s_add_i32 s56, 0, 0x14000
	s_add_i32 m0, s42, 0xc000
	v_lshl_add_u64 v[194:195], s[8:9], 0, v[178:179]
	global_load_lds_dwordx4 v[194:195], off
	s_add_i32 m0, s42, 0xe000
	v_lshl_add_u64 v[194:195], s[8:9], 0, v[180:181]
	global_load_lds_dwordx4 v[194:195], off
	s_waitcnt vmcnt(8) lgkmcnt(0)
	s_barrier
	s_setprio 1
	v_mfma_f32_16x16x32_bf16 v[128:131], v[132:135], v[164:167], v[128:131]
	v_mfma_f32_16x16x32_bf16 v[124:127], v[140:143], v[164:167], v[124:127]
	v_mfma_f32_16x16x32_bf16 v[112:115], v[132:135], v[186:189], v[112:115]
	v_mfma_f32_16x16x32_bf16 v[108:111], v[140:143], v[186:189], v[108:111]
	v_mfma_f32_16x16x32_bf16 v[96:99], v[132:135], v[208:211], v[96:99]
	v_mfma_f32_16x16x32_bf16 v[92:95], v[140:143], v[208:211], v[92:95]
	v_mfma_f32_16x16x32_bf16 v[80:83], v[132:135], v[216:219], v[80:83]
	v_mfma_f32_16x16x32_bf16 v[76:79], v[140:143], v[216:219], v[76:79]
	v_mfma_f32_16x16x32_bf16 v[128:131], v[136:139], v[182:185], v[128:131]
	v_mfma_f32_16x16x32_bf16 v[124:127], v[144:147], v[182:185], v[124:127]
	v_mfma_f32_16x16x32_bf16 v[112:115], v[136:139], v[190:193], v[112:115]
	v_mfma_f32_16x16x32_bf16 v[108:111], v[144:147], v[190:193], v[108:111]
	v_mfma_f32_16x16x32_bf16 v[96:99], v[136:139], v[212:215], v[96:99]
	v_mfma_f32_16x16x32_bf16 v[92:95], v[144:147], v[212:215], v[92:95]
	v_mfma_f32_16x16x32_bf16 v[80:83], v[136:139], v[220:223], v[80:83]
	v_mfma_f32_16x16x32_bf16 v[76:79], v[144:147], v[220:223], v[76:79]
	s_setprio 0
	s_setprio 1
	v_mfma_f32_16x16x32_bf16 v[120:123], v[148:151], v[164:167], v[120:123]
	v_mfma_f32_16x16x32_bf16 v[116:119], v[156:159], v[164:167], v[116:119]
	v_mfma_f32_16x16x32_bf16 v[104:107], v[148:151], v[186:189], v[104:107]
	v_mfma_f32_16x16x32_bf16 v[100:103], v[156:159], v[186:189], v[100:103]
	v_mfma_f32_16x16x32_bf16 v[88:91], v[148:151], v[208:211], v[88:91]
	v_mfma_f32_16x16x32_bf16 v[84:87], v[156:159], v[208:211], v[84:87]
	v_mfma_f32_16x16x32_bf16 v[72:75], v[148:151], v[216:219], v[72:75]
	v_mfma_f32_16x16x32_bf16 v[68:71], v[156:159], v[216:219], v[68:71]
	v_mfma_f32_16x16x32_bf16 v[120:123], v[152:155], v[182:185], v[120:123]
	v_mfma_f32_16x16x32_bf16 v[116:119], v[160:163], v[182:185], v[116:119]
	v_mfma_f32_16x16x32_bf16 v[104:107], v[152:155], v[190:193], v[104:107]
	v_mfma_f32_16x16x32_bf16 v[100:103], v[160:163], v[190:193], v[100:103]
	v_mfma_f32_16x16x32_bf16 v[88:91], v[152:155], v[212:215], v[88:91]
	v_mfma_f32_16x16x32_bf16 v[84:87], v[160:163], v[212:215], v[84:87]
	v_mfma_f32_16x16x32_bf16 v[72:75], v[152:155], v[220:223], v[72:75]
	v_mfma_f32_16x16x32_bf16 v[68:71], v[160:163], v[220:223], v[68:71]
	s_setprio 0
	s_barrier
	ds_read_b128 v[164:167], v205 offset:16384
	ds_read_b128 v[182:185], v205 offset:17408
	ds_read_b128 v[186:189], v205 offset:18432
	ds_read_b128 v[190:193], v205 offset:19456
	ds_read_b128 v[208:211], v205 offset:20480
	ds_read_b128 v[212:215], v205 offset:21504
	ds_read_b128 v[216:219], v205 offset:22528
	ds_read_b128 v[220:223], v205 offset:23552
	s_add_i32 s53, s53, s41
	s_mov_b32 m0, s53
	v_lshl_add_u64 v[194:195], s[28:29], 0, v[168:169]
	global_load_lds_dwordx4 v[194:195], off
	s_add_i32 m0, s53, 0x2000
	s_add_u32 s54, s28, 0x40000
	v_lshl_add_u64 v[202:203], s[28:29], 0, v[172:173]
	s_addc_u32 s55, s29, 0
	s_add_i32 s53, s56, s41
	global_load_lds_dwordx4 v[202:203], off
	v_lshl_add_u64 v[224:225], s[54:55], 0, v[168:169]
	s_mov_b32 m0, s53
	v_lshl_add_u64 v[226:227], s[30:31], 0, v[170:171]
	global_load_lds_dwordx4 v[224:225], off
	s_add_i32 m0, s53, 0x2000
	v_lshl_add_u64 v[224:225], s[54:55], 0, v[172:173]
	global_load_lds_dwordx4 v[224:225], off
	s_mov_b32 m0, s42
	v_lshl_add_u64 v[224:225], s[30:31], 0, v[0:1]
	global_load_lds_dwordx4 v[224:225], off
	s_mov_b32 m0, s43
	s_add_i32 s53, 0, 0x18000
	global_load_lds_dwordx4 v[226:227], off
	s_waitcnt vmcnt(8) lgkmcnt(0)
	s_barrier
; #define PG8_STAGE(bufoff, gbase, voff) do { _Pragma("unroll") for (int _i = 0; _i < 2; ++_i) \
;         __builtin_amdgcn_global_load_lds((const unsigned*)((const char*)(gbase) + (voff)[_i]), (PG8_LAS unsigned*)(lds + (bufoff) + ldsw + _i * 8192), 16, 0, 0); } while (0)
; #define PG8_LDA(dst, b, h) do { _Pragma("unroll") for (int m = 0; m < 4; ++m) _Pragma("unroll") for (int k = 0; k < 2; ++k) dst[m][k] = *(const PG8_LAS bf16x8*)(lds + PG8_SA(b, h) + aoff + m * 2048 + k * 1024); } while (0)
; #define PG8_LDB(dst, b, h) do { _Pragma("unroll") for (int n = 0; n < 2; ++n) _Pragma("unroll") for (int k = 0; k < 2; ++k) dst[n][k] = *(const PG8_LAS bf16x8*)(lds + PG8_SB(b, h) + boff + n * 2048 + k * 1024); } while (0)
; #define PG8_MMA(ai, bj, At, Bt) do { __builtin_amdgcn_s_setprio(1); _Pragma("unroll") for (int m = 0; m < 4; ++m) _Pragma("unroll") for (int n = 0; n < 2; ++n) _Pragma("unroll") for (int k = 0; k < 2; ++k) \
;         acc[ai][bj][m][n] = __builtin_amdgcn_mfma_f32_16x16x32_bf16(Bt[n][k], At[m][k], acc[ai][bj][m][n], 0, 0, 0); __builtin_amdgcn_s_setprio(0); } while (0)
; #define PG8_WAIT_V(n) asm volatile("s_waitcnt vmcnt(" #n ")" ::: "memory")
; #define PG8_WAIT_L(n) asm volatile("s_waitcnt lgkmcnt(" #n ")" ::: "memory")
; #define PG8_BAR __builtin_amdgcn_s_barrier()
; #define PG8_SCHED __builtin_amdgcn_sched_barrier(0)
; template <class Epi, class Sched, bool ALIGN_EPI = false, bool SP2 = false>
; __device__ __forceinline__ void gemm_phase(PG8_LAS unsigned char* lds, const Gemm g, const Sched& S, const Epi& E) {
;     ...
;             PG8_WAIT_V(8); PG8_WAIT_L(0); PG8_BAR; PG8_MMA(1, 0, At, B0); PG8_MMA(1, 1, At, B1); PG8_BAR; PG8_SCHED;
;             PG8_LDB(B0, 1, 0); PG8_LDB(B1, 1, 1); PG8_SCHED; PG8_LDA(At, 1, 0); PG8_STAGE(PG8_SA(0, 1), a2 + hstep, voffA);
;             PG8_WAIT_V(8); PG8_WAIT_L(0); PG8_BAR; PG8_MMA(0, 0, At, B0); PG8_MMA(0, 1, At, B1); PG8_BAR; PG8_SCHED;
	s_setprio 1
	v_mfma_f32_16x16x32_bf16 v[64:67], v[132:135], v[164:167], v[64:67]
	v_mfma_f32_16x16x32_bf16 v[60:63], v[140:143], v[164:167], v[60:63]
	v_mfma_f32_16x16x32_bf16 v[48:51], v[132:135], v[186:189], v[48:51]
	v_mfma_f32_16x16x32_bf16 v[44:47], v[140:143], v[186:189], v[44:47]
	v_mfma_f32_16x16x32_bf16 v[32:35], v[132:135], v[208:211], v[32:35]
	v_mfma_f32_16x16x32_bf16 v[28:31], v[140:143], v[208:211], v[28:31]
	v_mfma_f32_16x16x32_bf16 v[16:19], v[132:135], v[216:219], v[16:19]
	v_mfma_f32_16x16x32_bf16 v[12:15], v[140:143], v[216:219], v[12:15]
	v_mfma_f32_16x16x32_bf16 v[64:67], v[136:139], v[182:185], v[64:67]
	v_mfma_f32_16x16x32_bf16 v[60:63], v[144:147], v[182:185], v[60:63]
	v_mfma_f32_16x16x32_bf16 v[48:51], v[136:139], v[190:193], v[48:51]
	v_mfma_f32_16x16x32_bf16 v[44:47], v[144:147], v[190:193], v[44:47]
	v_mfma_f32_16x16x32_bf16 v[32:35], v[136:139], v[212:215], v[32:35]
	v_mfma_f32_16x16x32_bf16 v[28:31], v[144:147], v[212:215], v[28:31]
	v_mfma_f32_16x16x32_bf16 v[16:19], v[136:139], v[220:223], v[16:19]
	v_mfma_f32_16x16x32_bf16 v[12:15], v[144:147], v[220:223], v[12:15]
	s_setprio 0
	s_setprio 1
	v_mfma_f32_16x16x32_bf16 v[56:59], v[148:151], v[164:167], v[56:59]
	v_mfma_f32_16x16x32_bf16 v[52:55], v[156:159], v[164:167], v[52:55]
	v_mfma_f32_16x16x32_bf16 v[40:43], v[148:151], v[186:189], v[40:43]
	v_mfma_f32_16x16x32_bf16 v[36:39], v[156:159], v[186:189], v[36:39]
	v_mfma_f32_16x16x32_bf16 v[24:27], v[148:151], v[208:211], v[24:27]
	v_mfma_f32_16x16x32_bf16 v[20:23], v[156:159], v[208:211], v[20:23]
	v_mfma_f32_16x16x32_bf16 v[8:11], v[148:151], v[216:219], v[8:11]
	v_mfma_f32_16x16x32_bf16 v[4:7], v[156:159], v[216:219], v[4:7]
	v_mfma_f32_16x16x32_bf16 v[56:59], v[152:155], v[182:185], v[56:59]
	v_mfma_f32_16x16x32_bf16 v[52:55], v[160:163], v[182:185], v[52:55]
	v_mfma_f32_16x16x32_bf16 v[40:43], v[152:155], v[190:193], v[40:43]
	v_mfma_f32_16x16x32_bf16 v[36:39], v[160:163], v[190:193], v[36:39]
	v_mfma_f32_16x16x32_bf16 v[24:27], v[152:155], v[212:215], v[24:27]
	v_mfma_f32_16x16x32_bf16 v[20:23], v[160:163], v[212:215], v[20:23]
	v_mfma_f32_16x16x32_bf16 v[8:11], v[152:155], v[220:223], v[8:11]
	v_mfma_f32_16x16x32_bf16 v[4:7], v[160:163], v[220:223], v[4:7]
	s_setprio 0
	s_barrier
	ds_read_b128 v[164:167], v205 offset:32768
	ds_read_b128 v[182:185], v205 offset:33792
	ds_read_b128 v[186:189], v205 offset:34816
	ds_read_b128 v[190:193], v205 offset:35840
	ds_read_b128 v[208:211], v205 offset:36864
	ds_read_b128 v[212:215], v205 offset:37888
	ds_read_b128 v[216:219], v205 offset:38912
	ds_read_b128 v[220:223], v205 offset:39936
	v_add_u32_e32 v144, 0x18000, v204
	v_add_u32_e32 v160, 0x1c000, v204
	ds_read_b128 v[132:135], v144
	ds_read_b128 v[136:139], v144 offset:1024
	ds_read_b128 v[140:143], v144 offset:2048
	ds_read_b128 v[144:147], v144 offset:3072
	ds_read_b128 v[148:151], v160
	ds_read_b128 v[152:155], v160 offset:1024
	ds_read_b128 v[156:159], v160 offset:2048
	ds_read_b128 v[160:163], v160 offset:3072
	s_add_i32 s54, 0, 0x1c000
	s_add_u32 s30, s30, 0x40000
	s_addc_u32 s31, s31, 0
	s_mov_b32 m0, s46
	v_lshl_add_u64 v[228:229], s[30:31], 0, v[0:1]
	global_load_lds_dwordx4 v[228:229], off
	s_mov_b32 m0, s47
	v_lshl_add_u64 v[228:229], s[30:31], 0, v[170:171]
	global_load_lds_dwordx4 v[228:229], off
	s_waitcnt vmcnt(8) lgkmcnt(0)
	s_barrier
	s_setprio 1
	v_mfma_f32_16x16x32_bf16 v[128:131], v[132:135], v[164:167], v[128:131]
	v_mfma_f32_16x16x32_bf16 v[124:127], v[140:143], v[164:167], v[124:127]
	v_mfma_f32_16x16x32_bf16 v[112:115], v[132:135], v[186:189], v[112:115]
	v_mfma_f32_16x16x32_bf16 v[108:111], v[140:143], v[186:189], v[108:111]
	v_mfma_f32_16x16x32_bf16 v[96:99], v[132:135], v[208:211], v[96:99]
	v_mfma_f32_16x16x32_bf16 v[92:95], v[140:143], v[208:211], v[92:95]
	v_mfma_f32_16x16x32_bf16 v[80:83], v[132:135], v[216:219], v[80:83]
	v_mfma_f32_16x16x32_bf16 v[76:79], v[140:143], v[216:219], v[76:79]
	v_mfma_f32_16x16x32_bf16 v[128:131], v[136:139], v[182:185], v[128:131]
	v_mfma_f32_16x16x32_bf16 v[124:127], v[144:147], v[182:185], v[124:127]
	v_mfma_f32_16x16x32_bf16 v[112:115], v[136:139], v[190:193], v[112:115]
	v_mfma_f32_16x16x32_bf16 v[108:111], v[144:147], v[190:193], v[108:111]
	v_mfma_f32_16x16x32_bf16 v[96:99], v[136:139], v[212:215], v[96:99]
	v_mfma_f32_16x16x32_bf16 v[92:95], v[144:147], v[212:215], v[92:95]
	v_mfma_f32_16x16x32_bf16 v[80:83], v[136:139], v[220:223], v[80:83]
	v_mfma_f32_16x16x32_bf16 v[76:79], v[144:147], v[220:223], v[76:79]
	s_setprio 0
	s_setprio 1
	v_mfma_f32_16x16x32_bf16 v[120:123], v[148:151], v[164:167], v[120:123]
	v_mfma_f32_16x16x32_bf16 v[116:119], v[156:159], v[164:167], v[116:119]
	v_mfma_f32_16x16x32_bf16 v[104:107], v[148:151], v[186:189], v[104:107]
	v_mfma_f32_16x16x32_bf16 v[100:103], v[156:159], v[186:189], v[100:103]
	v_mfma_f32_16x16x32_bf16 v[88:91], v[148:151], v[208:211], v[88:91]
	v_mfma_f32_16x16x32_bf16 v[84:87], v[156:159], v[208:211], v[84:87]
	v_mfma_f32_16x16x32_bf16 v[72:75], v[148:151], v[216:219], v[72:75]
	v_mfma_f32_16x16x32_bf16 v[68:71], v[156:159], v[216:219], v[68:71]
	v_mfma_f32_16x16x32_bf16 v[120:123], v[152:155], v[182:185], v[120:123]
	v_mfma_f32_16x16x32_bf16 v[116:119], v[160:163], v[182:185], v[116:119]
	v_mfma_f32_16x16x32_bf16 v[104:107], v[152:155], v[190:193], v[104:107]
	v_mfma_f32_16x16x32_bf16 v[100:103], v[160:163], v[190:193], v[100:103]
	v_mfma_f32_16x16x32_bf16 v[88:91], v[152:155], v[212:215], v[88:91]
	v_mfma_f32_16x16x32_bf16 v[84:87], v[160:163], v[212:215], v[84:87]
	v_mfma_f32_16x16x32_bf16 v[72:75], v[152:155], v[220:223], v[72:75]
	v_mfma_f32_16x16x32_bf16 v[68:71], v[160:163], v[220:223], v[68:71]
	s_setprio 0
	s_barrier
; #define PG8_STAGE(bufoff, gbase, voff) do { _Pragma("unroll") for (int _i = 0; _i < 2; ++_i) \
;         __builtin_amdgcn_global_load_lds((const unsigned*)((const char*)(gbase) + (voff)[_i]), (PG8_LAS unsigned*)(lds + (bufoff) + ldsw + _i * 8192), 16, 0, 0); } while (0)
; #define PG8_LDA(dst, b, h) do { _Pragma("unroll") for (int m = 0; m < 4; ++m) _Pragma("unroll") for (int k = 0; k < 2; ++k) dst[m][k] = *(const PG8_LAS bf16x8*)(lds + PG8_SA(b, h) + aoff + m * 2048 + k * 1024); } while (0)
; #define PG8_MMA(ai, bj, At, Bt) do { __builtin_amdgcn_s_setprio(1); _Pragma("unroll") for (int m = 0; m < 4; ++m) _Pragma("unroll") for (int n = 0; n < 2; ++n) _Pragma("unroll") for (int k = 0; k < 2; ++k) \
;         acc[ai][bj][m][n] = __builtin_amdgcn_mfma_f32_16x16x32_bf16(Bt[n][k], At[m][k], acc[ai][bj][m][n], 0, 0, 0); __builtin_amdgcn_s_setprio(0); } while (0)
; #define PG8_WAIT_V(n) asm volatile("s_waitcnt vmcnt(" #n ")" ::: "memory")
; #define PG8_WAIT_L(n) asm volatile("s_waitcnt lgkmcnt(" #n ")" ::: "memory")
; #define PG8_BAR __builtin_amdgcn_s_barrier()
; #define PG8_SCHED __builtin_amdgcn_sched_barrier(0)
; template <class Epi, class Sched, bool ALIGN_EPI = false, bool SP2 = false>
; __device__ __forceinline__ void gemm_phase(PG8_LAS unsigned char* lds, const Gemm g, const Sched& S, const Epi& E) {
;     ...
;             PG8_LDA(At, 1, 1); PG8_STAGE(PG8_SB(1, 0), b3, voffB); PG8_STAGE(PG8_SB(1, 1), b3 + hstep, voffB); PG8_STAGE(PG8_SA(1, 0), a3, voffA);
;             PG8_WAIT_V(8); PG8_WAIT_L(0); PG8_BAR; PG8_MMA(1, 0, At, B0); PG8_MMA(1, 1, At, B1); PG8_BAR; PG8_SCHED;
;     ...
;         if constexpr (ALIGN_EPI) { if (wr == 0) PG8_BAR; }
	ds_read_b128 v[164:167], v205 offset:49152
	ds_read_b128 v[182:185], v205 offset:50176
	ds_read_b128 v[186:189], v205 offset:51200
	ds_read_b128 v[190:193], v205 offset:52224
	ds_read_b128 v[208:211], v205 offset:53248
	ds_read_b128 v[212:215], v205 offset:54272
	ds_read_b128 v[216:219], v205 offset:55296
	ds_read_b128 v[220:223], v205 offset:56320
	s_add_i32 s30, s53, s41
	s_mov_b32 m0, s30
	v_lshl_add_u64 v[194:195], v[194:195], 0, s[82:83]
	global_load_lds_dwordx4 v[194:195], off
	s_add_i32 m0, s30, 0x2000
	s_add_u32 s28, s28, 0x40080
	v_lshl_add_u64 v[194:195], v[202:203], 0, s[82:83]
	s_addc_u32 s29, s29, 0
	s_add_i32 s30, s54, s41
	global_load_lds_dwordx4 v[194:195], off
	s_mov_b32 m0, s30
	v_lshl_add_u64 v[194:195], s[28:29], 0, v[168:169]
	global_load_lds_dwordx4 v[194:195], off
	s_add_i32 m0, s30, 0x2000
	v_lshl_add_u64 v[194:195], s[28:29], 0, v[172:173]
	global_load_lds_dwordx4 v[194:195], off
	s_mov_b32 m0, s50
	v_lshl_add_u64 v[194:195], v[224:225], 0, s[82:83]
	global_load_lds_dwordx4 v[194:195], off
	s_mov_b32 m0, s51
	v_lshl_add_u64 v[194:195], v[226:227], 0, s[82:83]
	global_load_lds_dwordx4 v[194:195], off
	s_waitcnt vmcnt(8) lgkmcnt(0)
	s_barrier
	s_setprio 1
	v_mfma_f32_16x16x32_bf16 v[64:67], v[132:135], v[164:167], v[64:67]
	v_mfma_f32_16x16x32_bf16 v[60:63], v[140:143], v[164:167], v[60:63]
	v_mfma_f32_16x16x32_bf16 v[48:51], v[132:135], v[186:189], v[48:51]
	v_mfma_f32_16x16x32_bf16 v[44:47], v[140:143], v[186:189], v[44:47]
	v_mfma_f32_16x16x32_bf16 v[32:35], v[132:135], v[208:211], v[32:35]
	v_mfma_f32_16x16x32_bf16 v[28:31], v[140:143], v[208:211], v[28:31]
	v_mfma_f32_16x16x32_bf16 v[16:19], v[132:135], v[216:219], v[16:19]
	v_mfma_f32_16x16x32_bf16 v[12:15], v[140:143], v[216:219], v[12:15]
	v_mfma_f32_16x16x32_bf16 v[64:67], v[136:139], v[182:185], v[64:67]
	v_mfma_f32_16x16x32_bf16 v[60:63], v[144:147], v[182:185], v[60:63]
	v_mfma_f32_16x16x32_bf16 v[48:51], v[136:139], v[190:193], v[48:51]
	v_mfma_f32_16x16x32_bf16 v[44:47], v[144:147], v[190:193], v[44:47]
	v_mfma_f32_16x16x32_bf16 v[32:35], v[136:139], v[212:215], v[32:35]
	v_mfma_f32_16x16x32_bf16 v[28:31], v[144:147], v[212:215], v[28:31]
	v_mfma_f32_16x16x32_bf16 v[16:19], v[136:139], v[220:223], v[16:19]
	v_mfma_f32_16x16x32_bf16 v[12:15], v[144:147], v[220:223], v[12:15]
	s_setprio 0
	s_setprio 1
	v_mfma_f32_16x16x32_bf16 v[56:59], v[148:151], v[164:167], v[56:59]
	v_mfma_f32_16x16x32_bf16 v[52:55], v[156:159], v[164:167], v[52:55]
	v_mfma_f32_16x16x32_bf16 v[40:43], v[148:151], v[186:189], v[40:43]
	v_mfma_f32_16x16x32_bf16 v[36:39], v[156:159], v[186:189], v[36:39]
	v_mfma_f32_16x16x32_bf16 v[24:27], v[148:151], v[208:211], v[24:27]
	v_mfma_f32_16x16x32_bf16 v[20:23], v[156:159], v[208:211], v[20:23]
	v_mfma_f32_16x16x32_bf16 v[8:11], v[148:151], v[216:219], v[8:11]
	v_mfma_f32_16x16x32_bf16 v[4:7], v[156:159], v[216:219], v[4:7]
	v_mfma_f32_16x16x32_bf16 v[56:59], v[152:155], v[182:185], v[56:59]
	v_mfma_f32_16x16x32_bf16 v[52:55], v[160:163], v[182:185], v[52:55]
	v_mfma_f32_16x16x32_bf16 v[40:43], v[152:155], v[190:193], v[40:43]
	v_mfma_f32_16x16x32_bf16 v[36:39], v[160:163], v[190:193], v[36:39]
	v_mfma_f32_16x16x32_bf16 v[24:27], v[152:155], v[212:215], v[24:27]
	v_mfma_f32_16x16x32_bf16 v[20:23], v[160:163], v[212:215], v[20:23]
	v_mfma_f32_16x16x32_bf16 v[8:11], v[152:155], v[220:223], v[8:11]
	v_mfma_f32_16x16x32_bf16 v[4:7], v[160:163], v[220:223], v[4:7]
	s_setprio 0
	s_barrier
	s_add_i32 s45, s45, 2
	s_add_u32 s8, s8, 0x100
	s_addc_u32 s9, s9, 0
	s_add_u32 s23, s23, 0x100
	s_addc_u32 s44, s44, 0
	s_cmp_gt_u32 s45, 13
	s_cbranch_scc0 .LBB0_100
	s_and_b64 vcc, exec, s[14:15]
	s_cbranch_vccz .LBB0_103
	s_barrier

; #define PG8_STAGE(bufoff, gbase, voff) do { _Pragma("unroll") for (int _i = 0; _i < 2; ++_i) \
;         __builtin_amdgcn_global_load_lds((const unsigned*)((const char*)(gbase) + (voff)[_i]), (PG8_LAS unsigned*)(lds + (bufoff) + ldsw + _i * 8192), 16, 0, 0); } while (0)
; #define PG8_LDA(dst, b, h) do { _Pragma("unroll") for (int m = 0; m < 4; ++m) _Pragma("unroll") for (int k = 0; k < 2; ++k) dst[m][k] = *(const PG8_LAS bf16x8*)(lds + PG8_SA(b, h) + aoff + m * 2048 + k * 1024); } while (0)
; #define PG8_LDB(dst, b, h) do { _Pragma("unroll") for (int n = 0; n < 2; ++n) _Pragma("unroll") for (int k = 0; k < 2; ++k) dst[n][k] = *(const PG8_LAS bf16x8*)(lds + PG8_SB(b, h) + boff + n * 2048 + k * 1024); } while (0)
; #define PG8_MMA(ai, bj, At, Bt) do { __builtin_amdgcn_s_setprio(1); _Pragma("unroll") for (int m = 0; m < 4; ++m) _Pragma("unroll") for (int n = 0; n < 2; ++n) _Pragma("unroll") for (int k = 0; k < 2; ++k) \
;         acc[ai][bj][m][n] = __builtin_amdgcn_mfma_f32_16x16x32_bf16(Bt[n][k], At[m][k], acc[ai][bj][m][n], 0, 0, 0); __builtin_amdgcn_s_setprio(0); } while (0)
; #define PG8_WAIT_V(n) asm volatile("s_waitcnt vmcnt(" #n ")" ::: "memory")
; #define PG8_BAR __builtin_amdgcn_s_barrier()
; template <class Epi, class Sched, bool ALIGN_EPI = false, bool SP2 = false>
; __device__ __forceinline__ void gemm_phase(PG8_LAS unsigned char* lds, const Gemm g, const Sched& S, const Epi& E) {
;     ...
;         for (int t = 0; t < nt; t += 2) {
;             const bool last = (t == nt - 2);
;             const char* a1 = cA + (size_t)(t + 1) * kstep;
;             const char* a2 = last ? nA : cA + (size_t)(t + 2) * kstep; const char* b2 = last ? nB : cB + (size_t)(t + 2) * kstep;
;             const char* a3 = a2 + kstep; const char* b3 = b2 + kstep;
;             if (last && has_next) S.a_ready(nxt);
;             if constexpr (SP2) {
;             PG8_LDB(B0, 0, 0); PG8_LDB(B1, 0, 1); PG8_SCHED; PG8_LDA(At, 0, 0); PG8_STAGE(PG8_SA(1, 1), a1 + hstep, voffA);
;             PG8_WAIT_V(8); PG8_WAIT_L(0); PG8_BAR; PG8_MMA(0, 0, At, B0); PG8_MMA(0, 1, At, B1); PG8_BAR; PG8_SCHED;
;             PG8_LDA(At, 0, 1); PG8_STAGE(PG8_SB(0, 0), b2, voffB); PG8_STAGE(PG8_SB(0, 1), b2 + hstep, voffB); PG8_STAGE(PG8_SA(0, 0), a2, voffA);
;             PG8_WAIT_V(8); PG8_WAIT_L(0); PG8_BAR; PG8_MMA(1, 0, At, B0); PG8_MMA(1, 1, At, B1); PG8_BAR; PG8_SCHED;
.LBB0_329:
	ds_read_b128 v[164:167], v253
	ds_read_b128 v[168:171], v253 offset:1024
	ds_read_b128 v[172:175], v253 offset:2048
	ds_read_b128 v[176:179], v253 offset:3072
	ds_read_b128 v[180:183], v253 offset:4096
	ds_read_b128 v[184:187], v253 offset:5120
	ds_read_b128 v[188:191], v253 offset:6144
	ds_read_b128 v[192:195], v253 offset:7168
	v_add_u32_e32 v128, 0x10000, v251
	v_add_u32_e32 v156, 0x14000, v251
	ds_read_b128 v[108:111], v128
	ds_read_b128 v[112:115], v128 offset:1024
	ds_read_b128 v[124:127], v128 offset:2048
	ds_read_b128 v[128:131], v128 offset:3072
	ds_read_b128 v[132:135], v156
	ds_read_b128 v[140:143], v156 offset:1024
	ds_read_b128 v[148:151], v156 offset:2048
	ds_read_b128 v[156:159], v156 offset:3072
	s_add_u32 s30, s28, 0xfffc0080
	s_addc_u32 s31, s29, -1
	s_add_i32 s52, 0, 0x10000
	s_cmp_eq_u32 s45, 12
	s_cselect_b32 s35, s3, s31
	s_cselect_b32 s34, s17, s30
	s_cselect_b32 s31, s19, s44
	s_cselect_b32 s30, s25, s27
	s_add_i32 s54, 0, 0x14000
	s_add_i32 m0, s42, 0xc000
	v_lshl_add_u64 v[212:213], s[28:29], 0, v[208:209]
	global_load_lds_dwordx4 v[212:213], off
	s_add_i32 m0, s42, 0xe000
	v_lshl_add_u64 v[212:213], s[28:29], 0, v[210:211]
	global_load_lds_dwordx4 v[212:213], off
	s_waitcnt vmcnt(8) lgkmcnt(0)
	s_barrier
	s_setprio 1
	v_mfma_f32_16x16x32_bf16 v[160:163], v[108:111], v[164:167], v[160:163]
	v_mfma_f32_16x16x32_bf16 v[152:155], v[124:127], v[164:167], v[152:155]
	v_mfma_f32_16x16x32_bf16 v[120:123], v[108:111], v[172:175], v[120:123]
	v_mfma_f32_16x16x32_bf16 v[116:119], v[124:127], v[172:175], v[116:119]
	v_mfma_f32_16x16x32_bf16 v[96:99], v[108:111], v[180:183], v[96:99]
	v_mfma_f32_16x16x32_bf16 v[92:95], v[124:127], v[180:183], v[92:95]
	v_mfma_f32_16x16x32_bf16 v[80:83], v[108:111], v[188:191], v[80:83]
	v_mfma_f32_16x16x32_bf16 v[76:79], v[124:127], v[188:191], v[76:79]
	v_mfma_f32_16x16x32_bf16 v[160:163], v[112:115], v[168:171], v[160:163]
	v_mfma_f32_16x16x32_bf16 v[152:155], v[128:131], v[168:171], v[152:155]
	v_mfma_f32_16x16x32_bf16 v[120:123], v[112:115], v[176:179], v[120:123]
	v_mfma_f32_16x16x32_bf16 v[116:119], v[128:131], v[176:179], v[116:119]
	v_mfma_f32_16x16x32_bf16 v[96:99], v[112:115], v[184:187], v[96:99]
	v_mfma_f32_16x16x32_bf16 v[92:95], v[128:131], v[184:187], v[92:95]
	v_mfma_f32_16x16x32_bf16 v[80:83], v[112:115], v[192:195], v[80:83]
	v_mfma_f32_16x16x32_bf16 v[76:79], v[128:131], v[192:195], v[76:79]
	s_setprio 0
	s_setprio 1
	v_mfma_f32_16x16x32_bf16 v[144:147], v[132:135], v[164:167], v[144:147]
	v_mfma_f32_16x16x32_bf16 v[136:139], v[148:151], v[164:167], v[136:139]
	v_mfma_f32_16x16x32_bf16 v[104:107], v[132:135], v[172:175], v[104:107]
	v_mfma_f32_16x16x32_bf16 v[100:103], v[148:151], v[172:175], v[100:103]
	v_mfma_f32_16x16x32_bf16 v[88:91], v[132:135], v[180:183], v[88:91]
	v_mfma_f32_16x16x32_bf16 v[84:87], v[148:151], v[180:183], v[84:87]
	v_mfma_f32_16x16x32_bf16 v[72:75], v[132:135], v[188:191], v[72:75]
	v_mfma_f32_16x16x32_bf16 v[68:71], v[148:151], v[188:191], v[68:71]
	v_mfma_f32_16x16x32_bf16 v[144:147], v[140:143], v[168:171], v[144:147]
	v_mfma_f32_16x16x32_bf16 v[136:139], v[156:159], v[168:171], v[136:139]
	v_mfma_f32_16x16x32_bf16 v[104:107], v[140:143], v[176:179], v[104:107]
	v_mfma_f32_16x16x32_bf16 v[100:103], v[156:159], v[176:179], v[100:103]
	v_mfma_f32_16x16x32_bf16 v[88:91], v[140:143], v[184:187], v[88:91]
	v_mfma_f32_16x16x32_bf16 v[84:87], v[156:159], v[184:187], v[84:87]
	v_mfma_f32_16x16x32_bf16 v[72:75], v[140:143], v[192:195], v[72:75]
	v_mfma_f32_16x16x32_bf16 v[68:71], v[156:159], v[192:195], v[68:71]
	s_setprio 0
	s_barrier
	ds_read_b128 v[164:167], v253 offset:16384
	ds_read_b128 v[168:171], v253 offset:17408
	ds_read_b128 v[172:175], v253 offset:18432
	ds_read_b128 v[176:179], v253 offset:19456
	ds_read_b128 v[180:183], v253 offset:20480
	ds_read_b128 v[184:187], v253 offset:21504
	ds_read_b128 v[188:191], v253 offset:22528
	ds_read_b128 v[192:195], v253 offset:23552
	s_add_i32 s52, s52, s41
	s_mov_b32 m0, s52
	v_lshl_add_u64 v[212:213], s[30:31], 0, v[202:203]
	global_load_lds_dwordx4 v[212:213], off
	s_add_i32 m0, s52, 0x2000
	s_add_u32 s52, s30, 0x40000
	v_lshl_add_u64 v[214:215], s[30:31], 0, v[206:207]
	s_addc_u32 s53, s31, 0
	s_add_i32 s54, s54, s41
	global_load_lds_dwordx4 v[214:215], off
	v_lshl_add_u64 v[216:217], s[52:53], 0, v[202:203]
	s_mov_b32 m0, s54
	v_lshl_add_u64 v[218:219], s[34:35], 0, v[204:205]
	global_load_lds_dwordx4 v[216:217], off
	s_add_i32 m0, s54, 0x2000
	v_lshl_add_u64 v[216:217], s[52:53], 0, v[206:207]
	global_load_lds_dwordx4 v[216:217], off
	s_mov_b32 m0, s42
	v_lshl_add_u64 v[216:217], s[34:35], 0, v[0:1]
	global_load_lds_dwordx4 v[216:217], off
	s_mov_b32 m0, s43
	s_add_i32 s52, 0, 0x18000
	global_load_lds_dwordx4 v[218:219], off
	s_waitcnt vmcnt(8) lgkmcnt(0)
	s_barrier
; #define PG8_STAGE(bufoff, gbase, voff) do { _Pragma("unroll") for (int _i = 0; _i < 2; ++_i) \
;         __builtin_amdgcn_global_load_lds((const unsigned*)((const char*)(gbase) + (voff)[_i]), (PG8_LAS unsigned*)(lds + (bufoff) + ldsw + _i * 8192), 16, 0, 0); } while (0)
; #define PG8_LDA(dst, b, h) do { _Pragma("unroll") for (int m = 0; m < 4; ++m) _Pragma("unroll") for (int k = 0; k < 2; ++k) dst[m][k] = *(const PG8_LAS bf16x8*)(lds + PG8_SA(b, h) + aoff + m * 2048 + k * 1024); } while (0)
; #define PG8_LDB(dst, b, h) do { _Pragma("unroll") for (int n = 0; n < 2; ++n) _Pragma("unroll") for (int k = 0; k < 2; ++k) dst[n][k] = *(const PG8_LAS bf16x8*)(lds + PG8_SB(b, h) + boff + n * 2048 + k * 1024); } while (0)
; #define PG8_MMA(ai, bj, At, Bt) do { __builtin_amdgcn_s_setprio(1); _Pragma("unroll") for (int m = 0; m < 4; ++m) _Pragma("unroll") for (int n = 0; n < 2; ++n) _Pragma("unroll") for (int k = 0; k < 2; ++k) \
;         acc[ai][bj][m][n] = __builtin_amdgcn_mfma_f32_16x16x32_bf16(Bt[n][k], At[m][k], acc[ai][bj][m][n], 0, 0, 0); __builtin_amdgcn_s_setprio(0); } while (0)
; #define PG8_WAIT_V(n) asm volatile("s_waitcnt vmcnt(" #n ")" ::: "memory")
; #define PG8_WAIT_L(n) asm volatile("s_waitcnt lgkmcnt(" #n ")" ::: "memory")
; #define PG8_BAR __builtin_amdgcn_s_barrier()
; #define PG8_SCHED __builtin_amdgcn_sched_barrier(0)
; template <class Epi, class Sched, bool ALIGN_EPI = false, bool SP2 = false>
; __device__ __forceinline__ void gemm_phase(PG8_LAS unsigned char* lds, const Gemm g, const Sched& S, const Epi& E) {
;     ...
;             PG8_WAIT_V(8); PG8_WAIT_L(0); PG8_BAR; PG8_MMA(1, 0, At, B0); PG8_MMA(1, 1, At, B1); PG8_BAR; PG8_SCHED;
;             PG8_LDB(B0, 1, 0); PG8_LDB(B1, 1, 1); PG8_SCHED; PG8_LDA(At, 1, 0); PG8_STAGE(PG8_SA(0, 1), a2 + hstep, voffA);
;             PG8_WAIT_V(8); PG8_WAIT_L(0); PG8_BAR; PG8_MMA(0, 0, At, B0); PG8_MMA(0, 1, At, B1); PG8_BAR; PG8_SCHED;
	s_setprio 1
	v_mfma_f32_16x16x32_bf16 v[64:67], v[108:111], v[164:167], v[64:67]
	v_mfma_f32_16x16x32_bf16 v[60:63], v[124:127], v[164:167], v[60:63]
	v_mfma_f32_16x16x32_bf16 v[48:51], v[108:111], v[172:175], v[48:51]
	v_mfma_f32_16x16x32_bf16 v[44:47], v[124:127], v[172:175], v[44:47]
	v_mfma_f32_16x16x32_bf16 v[32:35], v[108:111], v[180:183], v[32:35]
	v_mfma_f32_16x16x32_bf16 v[28:31], v[124:127], v[180:183], v[28:31]
	v_mfma_f32_16x16x32_bf16 v[16:19], v[108:111], v[188:191], v[16:19]
	v_mfma_f32_16x16x32_bf16 v[12:15], v[124:127], v[188:191], v[12:15]
	v_mfma_f32_16x16x32_bf16 v[64:67], v[112:115], v[168:171], v[64:67]
	v_mfma_f32_16x16x32_bf16 v[60:63], v[128:131], v[168:171], v[60:63]
	v_mfma_f32_16x16x32_bf16 v[48:51], v[112:115], v[176:179], v[48:51]
	v_mfma_f32_16x16x32_bf16 v[44:47], v[128:131], v[176:179], v[44:47]
	v_mfma_f32_16x16x32_bf16 v[32:35], v[112:115], v[184:187], v[32:35]
	v_mfma_f32_16x16x32_bf16 v[28:31], v[128:131], v[184:187], v[28:31]
	v_mfma_f32_16x16x32_bf16 v[16:19], v[112:115], v[192:195], v[16:19]
	v_mfma_f32_16x16x32_bf16 v[12:15], v[128:131], v[192:195], v[12:15]
	s_setprio 0
	s_setprio 1
	v_mfma_f32_16x16x32_bf16 v[56:59], v[132:135], v[164:167], v[56:59]
	v_mfma_f32_16x16x32_bf16 v[52:55], v[148:151], v[164:167], v[52:55]
	v_mfma_f32_16x16x32_bf16 v[40:43], v[132:135], v[172:175], v[40:43]
	v_mfma_f32_16x16x32_bf16 v[36:39], v[148:151], v[172:175], v[36:39]
	v_mfma_f32_16x16x32_bf16 v[24:27], v[132:135], v[180:183], v[24:27]
	v_mfma_f32_16x16x32_bf16 v[20:23], v[148:151], v[180:183], v[20:23]
	v_mfma_f32_16x16x32_bf16 v[8:11], v[132:135], v[188:191], v[8:11]
	v_mfma_f32_16x16x32_bf16 v[4:7], v[148:151], v[188:191], v[4:7]
	v_mfma_f32_16x16x32_bf16 v[56:59], v[140:143], v[168:171], v[56:59]
	v_mfma_f32_16x16x32_bf16 v[52:55], v[156:159], v[168:171], v[52:55]
	v_mfma_f32_16x16x32_bf16 v[40:43], v[140:143], v[176:179], v[40:43]
	v_mfma_f32_16x16x32_bf16 v[36:39], v[156:159], v[176:179], v[36:39]
	v_mfma_f32_16x16x32_bf16 v[24:27], v[140:143], v[184:187], v[24:27]
	v_mfma_f32_16x16x32_bf16 v[20:23], v[156:159], v[184:187], v[20:23]
	v_mfma_f32_16x16x32_bf16 v[8:11], v[140:143], v[192:195], v[8:11]
	v_mfma_f32_16x16x32_bf16 v[4:7], v[156:159], v[192:195], v[4:7]
	s_setprio 0
	s_barrier
	ds_read_b128 v[164:167], v253 offset:32768
	ds_read_b128 v[168:171], v253 offset:33792
	ds_read_b128 v[172:175], v253 offset:34816
	ds_read_b128 v[176:179], v253 offset:35840
	ds_read_b128 v[180:183], v253 offset:36864
	ds_read_b128 v[184:187], v253 offset:37888
	ds_read_b128 v[188:191], v253 offset:38912
	ds_read_b128 v[192:195], v253 offset:39936
	v_add_u32_e32 v128, 0x18000, v251
	v_add_u32_e32 v156, 0x1c000, v251
	ds_read_b128 v[108:111], v128
	ds_read_b128 v[112:115], v128 offset:1024
	ds_read_b128 v[124:127], v128 offset:2048
	ds_read_b128 v[128:131], v128 offset:3072
	ds_read_b128 v[132:135], v156
	ds_read_b128 v[140:143], v156 offset:1024
	ds_read_b128 v[148:151], v156 offset:2048
	ds_read_b128 v[156:159], v156 offset:3072
	s_add_i32 s53, 0, 0x1c000
	s_add_u32 s34, s34, 0x40000
	s_addc_u32 s35, s35, 0
	s_mov_b32 m0, s46
	v_lshl_add_u64 v[220:221], s[34:35], 0, v[0:1]
	global_load_lds_dwordx4 v[220:221], off
	s_mov_b32 m0, s47
	v_lshl_add_u64 v[220:221], s[34:35], 0, v[204:205]
	global_load_lds_dwordx4 v[220:221], off
	s_waitcnt vmcnt(8) lgkmcnt(0)
	s_barrier
	s_setprio 1
	v_mfma_f32_16x16x32_bf16 v[160:163], v[108:111], v[164:167], v[160:163]
	v_mfma_f32_16x16x32_bf16 v[152:155], v[124:127], v[164:167], v[152:155]
	v_mfma_f32_16x16x32_bf16 v[120:123], v[108:111], v[172:175], v[120:123]
	v_mfma_f32_16x16x32_bf16 v[116:119], v[124:127], v[172:175], v[116:119]
	v_mfma_f32_16x16x32_bf16 v[96:99], v[108:111], v[180:183], v[96:99]
	v_mfma_f32_16x16x32_bf16 v[92:95], v[124:127], v[180:183], v[92:95]
	v_mfma_f32_16x16x32_bf16 v[80:83], v[108:111], v[188:191], v[80:83]
	v_mfma_f32_16x16x32_bf16 v[76:79], v[124:127], v[188:191], v[76:79]
	v_mfma_f32_16x16x32_bf16 v[160:163], v[112:115], v[168:171], v[160:163]
	v_mfma_f32_16x16x32_bf16 v[152:155], v[128:131], v[168:171], v[152:155]
	v_mfma_f32_16x16x32_bf16 v[120:123], v[112:115], v[176:179], v[120:123]
	v_mfma_f32_16x16x32_bf16 v[116:119], v[128:131], v[176:179], v[116:119]
	v_mfma_f32_16x16x32_bf16 v[96:99], v[112:115], v[184:187], v[96:99]
	v_mfma_f32_16x16x32_bf16 v[92:95], v[128:131], v[184:187], v[92:95]
	v_mfma_f32_16x16x32_bf16 v[80:83], v[112:115], v[192:195], v[80:83]
	v_mfma_f32_16x16x32_bf16 v[76:79], v[128:131], v[192:195], v[76:79]
	s_setprio 0
	s_setprio 1
	v_mfma_f32_16x16x32_bf16 v[144:147], v[132:135], v[164:167], v[144:147]
	v_mfma_f32_16x16x32_bf16 v[136:139], v[148:151], v[164:167], v[136:139]
	v_mfma_f32_16x16x32_bf16 v[104:107], v[132:135], v[172:175], v[104:107]
	v_mfma_f32_16x16x32_bf16 v[100:103], v[148:151], v[172:175], v[100:103]
	v_mfma_f32_16x16x32_bf16 v[88:91], v[132:135], v[180:183], v[88:91]
	v_mfma_f32_16x16x32_bf16 v[84:87], v[148:151], v[180:183], v[84:87]
	v_mfma_f32_16x16x32_bf16 v[72:75], v[132:135], v[188:191], v[72:75]
	v_mfma_f32_16x16x32_bf16 v[68:71], v[148:151], v[188:191], v[68:71]
	v_mfma_f32_16x16x32_bf16 v[144:147], v[140:143], v[168:171], v[144:147]
	v_mfma_f32_16x16x32_bf16 v[136:139], v[156:159], v[168:171], v[136:139]
	v_mfma_f32_16x16x32_bf16 v[104:107], v[140:143], v[176:179], v[104:107]
	v_mfma_f32_16x16x32_bf16 v[100:103], v[156:159], v[176:179], v[100:103]
	v_mfma_f32_16x16x32_bf16 v[88:91], v[140:143], v[184:187], v[88:91]
	v_mfma_f32_16x16x32_bf16 v[84:87], v[156:159], v[184:187], v[84:87]
	v_mfma_f32_16x16x32_bf16 v[72:75], v[140:143], v[192:195], v[72:75]
	v_mfma_f32_16x16x32_bf16 v[68:71], v[156:159], v[192:195], v[68:71]
	s_setprio 0
	s_barrier
; #define PG8_STAGE(bufoff, gbase, voff) do { _Pragma("unroll") for (int _i = 0; _i < 2; ++_i) \
;         __builtin_amdgcn_global_load_lds((const unsigned*)((const char*)(gbase) + (voff)[_i]), (PG8_LAS unsigned*)(lds + (bufoff) + ldsw + _i * 8192), 16, 0, 0); } while (0)
; #define PG8_LDA(dst, b, h) do { _Pragma("unroll") for (int m = 0; m < 4; ++m) _Pragma("unroll") for (int k = 0; k < 2; ++k) dst[m][k] = *(const PG8_LAS bf16x8*)(lds + PG8_SA(b, h) + aoff + m * 2048 + k * 1024); } while (0)
; #define PG8_MMA(ai, bj, At, Bt) do { __builtin_amdgcn_s_setprio(1); _Pragma("unroll") for (int m = 0; m < 4; ++m) _Pragma("unroll") for (int n = 0; n < 2; ++n) _Pragma("unroll") for (int k = 0; k < 2; ++k) \
;         acc[ai][bj][m][n] = __builtin_amdgcn_mfma_f32_16x16x32_bf16(Bt[n][k], At[m][k], acc[ai][bj][m][n], 0, 0, 0); __builtin_amdgcn_s_setprio(0); } while (0)
; #define PG8_WAIT_V(n) asm volatile("s_waitcnt vmcnt(" #n ")" ::: "memory")
; #define PG8_WAIT_L(n) asm volatile("s_waitcnt lgkmcnt(" #n ")" ::: "memory")
; #define PG8_BAR __builtin_amdgcn_s_barrier()
; #define PG8_SCHED __builtin_amdgcn_sched_barrier(0)
; template <class Epi, class Sched, bool ALIGN_EPI = false, bool SP2 = false>
; __device__ __forceinline__ void gemm_phase(PG8_LAS unsigned char* lds, const Gemm g, const Sched& S, const Epi& E) {
;     ...
;             PG8_LDA(At, 1, 1); PG8_STAGE(PG8_SB(1, 0), b3, voffB); PG8_STAGE(PG8_SB(1, 1), b3 + hstep, voffB); PG8_STAGE(PG8_SA(1, 0), a3, voffA);
;             PG8_WAIT_V(8); PG8_WAIT_L(0); PG8_BAR; PG8_MMA(1, 0, At, B0); PG8_MMA(1, 1, At, B1); PG8_BAR; PG8_SCHED;
;     ...
;         if constexpr (ALIGN_EPI) { if (wr == 0) PG8_BAR; }
	ds_read_b128 v[164:167], v253 offset:49152
	ds_read_b128 v[168:171], v253 offset:50176
	ds_read_b128 v[172:175], v253 offset:51200
	ds_read_b128 v[176:179], v253 offset:52224
	ds_read_b128 v[180:183], v253 offset:53248
	ds_read_b128 v[184:187], v253 offset:54272
	ds_read_b128 v[188:191], v253 offset:55296
	ds_read_b128 v[192:195], v253 offset:56320
	s_add_i32 s34, s52, s41
	s_mov_b32 m0, s34
	v_lshl_add_u64 v[212:213], v[212:213], 0, s[82:83]
	global_load_lds_dwordx4 v[212:213], off
	s_add_i32 m0, s34, 0x2000
	s_add_u32 s30, s30, 0x40080
	v_lshl_add_u64 v[212:213], v[214:215], 0, s[82:83]
	s_addc_u32 s31, s31, 0
	s_add_i32 s34, s53, s41
	global_load_lds_dwordx4 v[212:213], off
	s_mov_b32 m0, s34
	v_lshl_add_u64 v[212:213], s[30:31], 0, v[202:203]
	global_load_lds_dwordx4 v[212:213], off
	s_add_i32 m0, s34, 0x2000
	v_lshl_add_u64 v[212:213], s[30:31], 0, v[206:207]
	global_load_lds_dwordx4 v[212:213], off
	s_mov_b32 m0, s49
	v_lshl_add_u64 v[212:213], v[216:217], 0, s[82:83]
	global_load_lds_dwordx4 v[212:213], off
	s_mov_b32 m0, s50
	v_lshl_add_u64 v[212:213], v[218:219], 0, s[82:83]
	global_load_lds_dwordx4 v[212:213], off
	s_waitcnt vmcnt(8) lgkmcnt(0)
	s_barrier
	s_setprio 1
	v_mfma_f32_16x16x32_bf16 v[64:67], v[108:111], v[164:167], v[64:67]
	v_mfma_f32_16x16x32_bf16 v[60:63], v[124:127], v[164:167], v[60:63]
	v_mfma_f32_16x16x32_bf16 v[48:51], v[108:111], v[172:175], v[48:51]
	v_mfma_f32_16x16x32_bf16 v[44:47], v[124:127], v[172:175], v[44:47]
	v_mfma_f32_16x16x32_bf16 v[32:35], v[108:111], v[180:183], v[32:35]
	v_mfma_f32_16x16x32_bf16 v[28:31], v[124:127], v[180:183], v[28:31]
	v_mfma_f32_16x16x32_bf16 v[16:19], v[108:111], v[188:191], v[16:19]
	v_mfma_f32_16x16x32_bf16 v[12:15], v[124:127], v[188:191], v[12:15]
	v_mfma_f32_16x16x32_bf16 v[64:67], v[112:115], v[168:171], v[64:67]
	v_mfma_f32_16x16x32_bf16 v[60:63], v[128:131], v[168:171], v[60:63]
	v_mfma_f32_16x16x32_bf16 v[48:51], v[112:115], v[176:179], v[48:51]
	v_mfma_f32_16x16x32_bf16 v[44:47], v[128:131], v[176:179], v[44:47]
	v_mfma_f32_16x16x32_bf16 v[32:35], v[112:115], v[184:187], v[32:35]
	v_mfma_f32_16x16x32_bf16 v[28:31], v[128:131], v[184:187], v[28:31]
	v_mfma_f32_16x16x32_bf16 v[16:19], v[112:115], v[192:195], v[16:19]
	v_mfma_f32_16x16x32_bf16 v[12:15], v[128:131], v[192:195], v[12:15]
	s_setprio 0
	s_setprio 1
	v_mfma_f32_16x16x32_bf16 v[56:59], v[132:135], v[164:167], v[56:59]
	v_mfma_f32_16x16x32_bf16 v[52:55], v[148:151], v[164:167], v[52:55]
	v_mfma_f32_16x16x32_bf16 v[40:43], v[132:135], v[172:175], v[40:43]
	v_mfma_f32_16x16x32_bf16 v[36:39], v[148:151], v[172:175], v[36:39]
	v_mfma_f32_16x16x32_bf16 v[24:27], v[132:135], v[180:183], v[24:27]
	v_mfma_f32_16x16x32_bf16 v[20:23], v[148:151], v[180:183], v[20:23]
	v_mfma_f32_16x16x32_bf16 v[8:11], v[132:135], v[188:191], v[8:11]
	v_mfma_f32_16x16x32_bf16 v[4:7], v[148:151], v[188:191], v[4:7]
	v_mfma_f32_16x16x32_bf16 v[56:59], v[140:143], v[168:171], v[56:59]
	v_mfma_f32_16x16x32_bf16 v[52:55], v[156:159], v[168:171], v[52:55]
	v_mfma_f32_16x16x32_bf16 v[40:43], v[140:143], v[176:179], v[40:43]
	v_mfma_f32_16x16x32_bf16 v[36:39], v[156:159], v[176:179], v[36:39]
	v_mfma_f32_16x16x32_bf16 v[24:27], v[140:143], v[184:187], v[24:27]
	v_mfma_f32_16x16x32_bf16 v[20:23], v[156:159], v[184:187], v[20:23]
	v_mfma_f32_16x16x32_bf16 v[8:11], v[140:143], v[192:195], v[8:11]
	v_mfma_f32_16x16x32_bf16 v[4:7], v[156:159], v[192:195], v[4:7]
	s_setprio 0
	s_barrier
	s_add_i32 s45, s45, 2
	s_add_u32 s28, s28, 0x100
	s_addc_u32 s29, s29, 0
	s_add_u32 s27, s27, 0x100
	s_addc_u32 s44, s44, 0
	s_cmp_gt_u32 s45, 13
	s_cbranch_scc0 .LBB0_329
	s_and_b64 vcc, exec, s[14:15]
	s_cbranch_vccz .LBB0_332
	s_barrier

; #define PG8_STAGE(bufoff, gbase, voff) do { _Pragma("unroll") for (int _i = 0; _i < 2; ++_i) \
;         __builtin_amdgcn_global_load_lds((const unsigned*)((const char*)(gbase) + (voff)[_i]), (PG8_LAS unsigned*)(lds + (bufoff) + ldsw + _i * 8192), 16, 0, 0); } while (0)
; #define PG8_LDA(dst, b, h) do { _Pragma("unroll") for (int m = 0; m < 4; ++m) _Pragma("unroll") for (int k = 0; k < 2; ++k) dst[m][k] = *(const PG8_LAS bf16x8*)(lds + PG8_SA(b, h) + aoff + m * 2048 + k * 1024); } while (0)
; #define PG8_LDB(dst, b, h) do { _Pragma("unroll") for (int n = 0; n < 2; ++n) _Pragma("unroll") for (int k = 0; k < 2; ++k) dst[n][k] = *(const PG8_LAS bf16x8*)(lds + PG8_SB(b, h) + boff + n * 2048 + k * 1024); } while (0)
; #define PG8_MMA(ai, bj, At, Bt) do { __builtin_amdgcn_s_setprio(1); _Pragma("unroll") for (int m = 0; m < 4; ++m) _Pragma("unroll") for (int n = 0; n < 2; ++n) _Pragma("unroll") for (int k = 0; k < 2; ++k) \
;         acc[ai][bj][m][n] = __builtin_amdgcn_mfma_f32_16x16x32_bf16(Bt[n][k], At[m][k], acc[ai][bj][m][n], 0, 0, 0); __builtin_amdgcn_s_setprio(0); } while (0)
; #define PG8_WAIT_V(n) asm volatile("s_waitcnt vmcnt(" #n ")" ::: "memory")
; #define PG8_BAR __builtin_amdgcn_s_barrier()
; template <class Epi, class Sched, bool ALIGN_EPI = false, bool SP2 = false>
; __device__ __forceinline__ void gemm_phase(PG8_LAS unsigned char* lds, const Gemm g, const Sched& S, const Epi& E) {
;     ...
;         for (int t = 0; t < nt; t += 2) {
;             const bool last = (t == nt - 2);
;             const char* a1 = cA + (size_t)(t + 1) * kstep;
;             const char* a2 = last ? nA : cA + (size_t)(t + 2) * kstep; const char* b2 = last ? nB : cB + (size_t)(t + 2) * kstep;
;             const char* a3 = a2 + kstep; const char* b3 = b2 + kstep;
;             if (last && has_next) S.a_ready(nxt);
;             if constexpr (SP2) {
;             PG8_LDB(B0, 0, 0); PG8_LDB(B1, 0, 1); PG8_SCHED; PG8_LDA(At, 0, 0); PG8_STAGE(PG8_SA(1, 1), a1 + hstep, voffA);
;             PG8_WAIT_V(8); PG8_WAIT_L(0); PG8_BAR; PG8_MMA(0, 0, At, B0); PG8_MMA(0, 1, At, B1); PG8_BAR; PG8_SCHED;
;             PG8_LDA(At, 0, 1); PG8_STAGE(PG8_SB(0, 0), b2, voffB); PG8_STAGE(PG8_SB(0, 1), b2 + hstep, voffB); PG8_STAGE(PG8_SA(0, 0), a2, voffA);
;             PG8_WAIT_V(8); PG8_WAIT_L(0); PG8_BAR; PG8_MMA(1, 0, At, B0); PG8_MMA(1, 1, At, B1); PG8_BAR; PG8_SCHED;
.LBB0_405:
	ds_read_b128 v[180:183], v166
	ds_read_b128 v[184:187], v166 offset:1024
	ds_read_b128 v[188:191], v166 offset:2048
	ds_read_b128 v[192:195], v166 offset:3072
	ds_read_b128 v[202:205], v166 offset:4096
	ds_read_b128 v[206:209], v166 offset:5120
	ds_read_b128 v[210:213], v166 offset:6144
	ds_read_b128 v[214:217], v166 offset:7168
	v_add_u32_e32 v156, 0x10000, v164
	v_add_u32_e32 v167, 0x14000, v164
	ds_read_b128 v[144:147], v156
	ds_read_b128 v[148:151], v156 offset:1024
	ds_read_b128 v[152:155], v156 offset:2048
	ds_read_b128 v[156:159], v156 offset:3072
	ds_read_b128 v[160:163], v167
	ds_read_b128 v[168:171], v167 offset:1024
	ds_read_b128 v[172:175], v167 offset:2048
	ds_read_b128 v[176:179], v167 offset:3072
	s_add_u32 s24, s8, 0xfffc0080
	s_addc_u32 s25, s9, -1
	s_add_i32 s47, 0, 0x10000
	s_cmp_eq_u32 s46, 12
	s_cselect_b32 s27, s7, s25
	s_cselect_b32 s26, s17, s24
	s_cselect_b32 s25, s19, s45
	s_cselect_b32 s24, s43, s44
	s_add_i32 s50, 0, 0x14000
	s_add_i32 m0, s37, 0xc000
	v_lshl_add_u64 v[198:199], s[8:9], 0, v[140:141]
	global_load_lds_dwordx4 v[198:199], off
	s_add_i32 m0, s37, 0xe000
	v_lshl_add_u64 v[198:199], s[8:9], 0, v[142:143]
	global_load_lds_dwordx4 v[198:199], off
	s_waitcnt vmcnt(8) lgkmcnt(0)
	s_barrier
	s_setprio 1
	v_mfma_f32_16x16x32_bf16 v[128:131], v[144:147], v[180:183], v[128:131]
	v_mfma_f32_16x16x32_bf16 v[120:123], v[152:155], v[180:183], v[120:123]
	v_mfma_f32_16x16x32_bf16 v[112:115], v[144:147], v[188:191], v[112:115]
	v_mfma_f32_16x16x32_bf16 v[104:107], v[152:155], v[188:191], v[104:107]
	v_mfma_f32_16x16x32_bf16 v[96:99], v[144:147], v[202:205], v[96:99]
	v_mfma_f32_16x16x32_bf16 v[88:91], v[152:155], v[202:205], v[88:91]
	v_mfma_f32_16x16x32_bf16 v[80:83], v[144:147], v[210:213], v[80:83]
	v_mfma_f32_16x16x32_bf16 v[72:75], v[152:155], v[210:213], v[72:75]
	v_mfma_f32_16x16x32_bf16 v[128:131], v[148:151], v[184:187], v[128:131]
	v_mfma_f32_16x16x32_bf16 v[120:123], v[156:159], v[184:187], v[120:123]
	v_mfma_f32_16x16x32_bf16 v[112:115], v[148:151], v[192:195], v[112:115]
	v_mfma_f32_16x16x32_bf16 v[104:107], v[156:159], v[192:195], v[104:107]
	v_mfma_f32_16x16x32_bf16 v[96:99], v[148:151], v[206:209], v[96:99]
	v_mfma_f32_16x16x32_bf16 v[88:91], v[156:159], v[206:209], v[88:91]
	v_mfma_f32_16x16x32_bf16 v[80:83], v[148:151], v[214:217], v[80:83]
	v_mfma_f32_16x16x32_bf16 v[72:75], v[156:159], v[214:217], v[72:75]
	s_setprio 0
	s_setprio 1
	v_mfma_f32_16x16x32_bf16 v[124:127], v[160:163], v[180:183], v[124:127]
	v_mfma_f32_16x16x32_bf16 v[116:119], v[172:175], v[180:183], v[116:119]
	v_mfma_f32_16x16x32_bf16 v[108:111], v[160:163], v[188:191], v[108:111]
	v_mfma_f32_16x16x32_bf16 v[100:103], v[172:175], v[188:191], v[100:103]
	v_mfma_f32_16x16x32_bf16 v[92:95], v[160:163], v[202:205], v[92:95]
	v_mfma_f32_16x16x32_bf16 v[84:87], v[172:175], v[202:205], v[84:87]
	v_mfma_f32_16x16x32_bf16 v[76:79], v[160:163], v[210:213], v[76:79]
	v_mfma_f32_16x16x32_bf16 v[68:71], v[172:175], v[210:213], v[68:71]
	v_mfma_f32_16x16x32_bf16 v[124:127], v[168:171], v[184:187], v[124:127]
	v_mfma_f32_16x16x32_bf16 v[116:119], v[176:179], v[184:187], v[116:119]
	v_mfma_f32_16x16x32_bf16 v[108:111], v[168:171], v[192:195], v[108:111]
	v_mfma_f32_16x16x32_bf16 v[100:103], v[176:179], v[192:195], v[100:103]
	v_mfma_f32_16x16x32_bf16 v[92:95], v[168:171], v[206:209], v[92:95]
	v_mfma_f32_16x16x32_bf16 v[84:87], v[176:179], v[206:209], v[84:87]
	v_mfma_f32_16x16x32_bf16 v[76:79], v[168:171], v[214:217], v[76:79]
	v_mfma_f32_16x16x32_bf16 v[68:71], v[176:179], v[214:217], v[68:71]
	s_setprio 0
	s_barrier
	ds_read_b128 v[180:183], v166 offset:16384
	ds_read_b128 v[184:187], v166 offset:17408
	ds_read_b128 v[188:191], v166 offset:18432
	ds_read_b128 v[192:195], v166 offset:19456
	ds_read_b128 v[202:205], v166 offset:20480
	ds_read_b128 v[206:209], v166 offset:21504
	ds_read_b128 v[210:213], v166 offset:22528
	ds_read_b128 v[214:217], v166 offset:23552
	s_add_i32 s47, s47, s35
	s_mov_b32 m0, s47
	v_lshl_add_u64 v[198:199], s[24:25], 0, v[134:135]
	global_load_lds_dwordx4 v[198:199], off
	s_add_i32 m0, s47, 0x2000
	s_add_u32 s48, s24, 0x40000
	v_lshl_add_u64 v[218:219], s[24:25], 0, v[0:1]
	s_addc_u32 s49, s25, 0
	s_add_i32 s47, s50, s35
	global_load_lds_dwordx4 v[218:219], off
	v_lshl_add_u64 v[220:221], s[48:49], 0, v[134:135]
	s_mov_b32 m0, s47
	v_lshl_add_u64 v[222:223], s[26:27], 0, v[132:133]
	global_load_lds_dwordx4 v[220:221], off
	s_add_i32 m0, s47, 0x2000
	v_lshl_add_u64 v[220:221], s[48:49], 0, v[0:1]
	global_load_lds_dwordx4 v[220:221], off
	s_mov_b32 m0, s37
	v_lshl_add_u64 v[220:221], s[26:27], 0, v[136:137]
	global_load_lds_dwordx4 v[220:221], off
	s_mov_b32 m0, s38
	s_add_i32 s47, 0, 0x18000
	global_load_lds_dwordx4 v[222:223], off
	s_waitcnt vmcnt(8) lgkmcnt(0)
	s_barrier
; #define PG8_STAGE(bufoff, gbase, voff) do { _Pragma("unroll") for (int _i = 0; _i < 2; ++_i) \
;         __builtin_amdgcn_global_load_lds((const unsigned*)((const char*)(gbase) + (voff)[_i]), (PG8_LAS unsigned*)(lds + (bufoff) + ldsw + _i * 8192), 16, 0, 0); } while (0)
; #define PG8_LDA(dst, b, h) do { _Pragma("unroll") for (int m = 0; m < 4; ++m) _Pragma("unroll") for (int k = 0; k < 2; ++k) dst[m][k] = *(const PG8_LAS bf16x8*)(lds + PG8_SA(b, h) + aoff + m * 2048 + k * 1024); } while (0)
; #define PG8_LDB(dst, b, h) do { _Pragma("unroll") for (int n = 0; n < 2; ++n) _Pragma("unroll") for (int k = 0; k < 2; ++k) dst[n][k] = *(const PG8_LAS bf16x8*)(lds + PG8_SB(b, h) + boff + n * 2048 + k * 1024); } while (0)
; #define PG8_MMA(ai, bj, At, Bt) do { __builtin_amdgcn_s_setprio(1); _Pragma("unroll") for (int m = 0; m < 4; ++m) _Pragma("unroll") for (int n = 0; n < 2; ++n) _Pragma("unroll") for (int k = 0; k < 2; ++k) \
;         acc[ai][bj][m][n] = __builtin_amdgcn_mfma_f32_16x16x32_bf16(Bt[n][k], At[m][k], acc[ai][bj][m][n], 0, 0, 0); __builtin_amdgcn_s_setprio(0); } while (0)
; #define PG8_WAIT_V(n) asm volatile("s_waitcnt vmcnt(" #n ")" ::: "memory")
; #define PG8_WAIT_L(n) asm volatile("s_waitcnt lgkmcnt(" #n ")" ::: "memory")
; #define PG8_BAR __builtin_amdgcn_s_barrier()
; #define PG8_SCHED __builtin_amdgcn_sched_barrier(0)
; template <class Epi, class Sched, bool ALIGN_EPI = false, bool SP2 = false>
; __device__ __forceinline__ void gemm_phase(PG8_LAS unsigned char* lds, const Gemm g, const Sched& S, const Epi& E) {
;     ...
;             PG8_WAIT_V(8); PG8_WAIT_L(0); PG8_BAR; PG8_MMA(1, 0, At, B0); PG8_MMA(1, 1, At, B1); PG8_BAR; PG8_SCHED;
;             PG8_LDB(B0, 1, 0); PG8_LDB(B1, 1, 1); PG8_SCHED; PG8_LDA(At, 1, 0); PG8_STAGE(PG8_SA(0, 1), a2 + hstep, voffA);
;             PG8_WAIT_V(8); PG8_WAIT_L(0); PG8_BAR; PG8_MMA(0, 0, At, B0); PG8_MMA(0, 1, At, B1); PG8_BAR; PG8_SCHED;
	s_setprio 1
	v_mfma_f32_16x16x32_bf16 v[64:67], v[144:147], v[180:183], v[64:67]
	v_mfma_f32_16x16x32_bf16 v[56:59], v[152:155], v[180:183], v[56:59]
	v_mfma_f32_16x16x32_bf16 v[48:51], v[144:147], v[188:191], v[48:51]
	v_mfma_f32_16x16x32_bf16 v[40:43], v[152:155], v[188:191], v[40:43]
	v_mfma_f32_16x16x32_bf16 v[32:35], v[144:147], v[202:205], v[32:35]
	v_mfma_f32_16x16x32_bf16 v[24:27], v[152:155], v[202:205], v[24:27]
	v_mfma_f32_16x16x32_bf16 v[16:19], v[144:147], v[210:213], v[16:19]
	v_mfma_f32_16x16x32_bf16 v[8:11], v[152:155], v[210:213], v[8:11]
	v_mfma_f32_16x16x32_bf16 v[64:67], v[148:151], v[184:187], v[64:67]
	v_mfma_f32_16x16x32_bf16 v[56:59], v[156:159], v[184:187], v[56:59]
	v_mfma_f32_16x16x32_bf16 v[48:51], v[148:151], v[192:195], v[48:51]
	v_mfma_f32_16x16x32_bf16 v[40:43], v[156:159], v[192:195], v[40:43]
	v_mfma_f32_16x16x32_bf16 v[32:35], v[148:151], v[206:209], v[32:35]
	v_mfma_f32_16x16x32_bf16 v[24:27], v[156:159], v[206:209], v[24:27]
	v_mfma_f32_16x16x32_bf16 v[16:19], v[148:151], v[214:217], v[16:19]
	v_mfma_f32_16x16x32_bf16 v[8:11], v[156:159], v[214:217], v[8:11]
	s_setprio 0
	s_setprio 1
	v_mfma_f32_16x16x32_bf16 v[60:63], v[160:163], v[180:183], v[60:63]
	v_mfma_f32_16x16x32_bf16 v[52:55], v[172:175], v[180:183], v[52:55]
	v_mfma_f32_16x16x32_bf16 v[44:47], v[160:163], v[188:191], v[44:47]
	v_mfma_f32_16x16x32_bf16 v[36:39], v[172:175], v[188:191], v[36:39]
	v_mfma_f32_16x16x32_bf16 v[28:31], v[160:163], v[202:205], v[28:31]
	v_mfma_f32_16x16x32_bf16 v[20:23], v[172:175], v[202:205], v[20:23]
	v_mfma_f32_16x16x32_bf16 v[12:15], v[160:163], v[210:213], v[12:15]
	v_mfma_f32_16x16x32_bf16 v[4:7], v[172:175], v[210:213], v[4:7]
	v_mfma_f32_16x16x32_bf16 v[60:63], v[168:171], v[184:187], v[60:63]
	v_mfma_f32_16x16x32_bf16 v[52:55], v[176:179], v[184:187], v[52:55]
	v_mfma_f32_16x16x32_bf16 v[44:47], v[168:171], v[192:195], v[44:47]
	v_mfma_f32_16x16x32_bf16 v[36:39], v[176:179], v[192:195], v[36:39]
	v_mfma_f32_16x16x32_bf16 v[28:31], v[168:171], v[206:209], v[28:31]
	v_mfma_f32_16x16x32_bf16 v[20:23], v[176:179], v[206:209], v[20:23]
	v_mfma_f32_16x16x32_bf16 v[12:15], v[168:171], v[214:217], v[12:15]
	v_mfma_f32_16x16x32_bf16 v[4:7], v[176:179], v[214:217], v[4:7]
	s_setprio 0
	s_barrier
	ds_read_b128 v[180:183], v166 offset:32768
	ds_read_b128 v[184:187], v166 offset:33792
	ds_read_b128 v[188:191], v166 offset:34816
	ds_read_b128 v[192:195], v166 offset:35840
	ds_read_b128 v[202:205], v166 offset:36864
	ds_read_b128 v[206:209], v166 offset:37888
	ds_read_b128 v[210:213], v166 offset:38912
	ds_read_b128 v[214:217], v166 offset:39936
	v_add_u32_e32 v156, 0x18000, v164
	v_add_u32_e32 v167, 0x1c000, v164
	ds_read_b128 v[144:147], v156
	ds_read_b128 v[148:151], v156 offset:1024
	ds_read_b128 v[152:155], v156 offset:2048
	ds_read_b128 v[156:159], v156 offset:3072
	ds_read_b128 v[160:163], v167
	ds_read_b128 v[168:171], v167 offset:1024
	ds_read_b128 v[172:175], v167 offset:2048
	ds_read_b128 v[176:179], v167 offset:3072
	s_add_i32 s48, 0, 0x1c000
	s_add_u32 s26, s26, 0x40000
	s_addc_u32 s27, s27, 0
	s_mov_b32 m0, s39
	v_lshl_add_u64 v[224:225], s[26:27], 0, v[136:137]
	global_load_lds_dwordx4 v[224:225], off
	s_mov_b32 m0, s40
	v_lshl_add_u64 v[224:225], s[26:27], 0, v[132:133]
	global_load_lds_dwordx4 v[224:225], off
	s_waitcnt vmcnt(8) lgkmcnt(0)
	s_barrier
	s_setprio 1
	v_mfma_f32_16x16x32_bf16 v[128:131], v[144:147], v[180:183], v[128:131]
	v_mfma_f32_16x16x32_bf16 v[120:123], v[152:155], v[180:183], v[120:123]
	v_mfma_f32_16x16x32_bf16 v[112:115], v[144:147], v[188:191], v[112:115]
	v_mfma_f32_16x16x32_bf16 v[104:107], v[152:155], v[188:191], v[104:107]
	v_mfma_f32_16x16x32_bf16 v[96:99], v[144:147], v[202:205], v[96:99]
	v_mfma_f32_16x16x32_bf16 v[88:91], v[152:155], v[202:205], v[88:91]
	v_mfma_f32_16x16x32_bf16 v[80:83], v[144:147], v[210:213], v[80:83]
	v_mfma_f32_16x16x32_bf16 v[72:75], v[152:155], v[210:213], v[72:75]
	v_mfma_f32_16x16x32_bf16 v[128:131], v[148:151], v[184:187], v[128:131]
	v_mfma_f32_16x16x32_bf16 v[120:123], v[156:159], v[184:187], v[120:123]
	v_mfma_f32_16x16x32_bf16 v[112:115], v[148:151], v[192:195], v[112:115]
	v_mfma_f32_16x16x32_bf16 v[104:107], v[156:159], v[192:195], v[104:107]
	v_mfma_f32_16x16x32_bf16 v[96:99], v[148:151], v[206:209], v[96:99]
	v_mfma_f32_16x16x32_bf16 v[88:91], v[156:159], v[206:209], v[88:91]
	v_mfma_f32_16x16x32_bf16 v[80:83], v[148:151], v[214:217], v[80:83]
	v_mfma_f32_16x16x32_bf16 v[72:75], v[156:159], v[214:217], v[72:75]
	s_setprio 0
	s_setprio 1
	v_mfma_f32_16x16x32_bf16 v[124:127], v[160:163], v[180:183], v[124:127]
	v_mfma_f32_16x16x32_bf16 v[116:119], v[172:175], v[180:183], v[116:119]
	v_mfma_f32_16x16x32_bf16 v[108:111], v[160:163], v[188:191], v[108:111]
	v_mfma_f32_16x16x32_bf16 v[100:103], v[172:175], v[188:191], v[100:103]
	v_mfma_f32_16x16x32_bf16 v[92:95], v[160:163], v[202:205], v[92:95]
	v_mfma_f32_16x16x32_bf16 v[84:87], v[172:175], v[202:205], v[84:87]
	v_mfma_f32_16x16x32_bf16 v[76:79], v[160:163], v[210:213], v[76:79]
	v_mfma_f32_16x16x32_bf16 v[68:71], v[172:175], v[210:213], v[68:71]
	v_mfma_f32_16x16x32_bf16 v[124:127], v[168:171], v[184:187], v[124:127]
	v_mfma_f32_16x16x32_bf16 v[116:119], v[176:179], v[184:187], v[116:119]
	v_mfma_f32_16x16x32_bf16 v[108:111], v[168:171], v[192:195], v[108:111]
	v_mfma_f32_16x16x32_bf16 v[100:103], v[176:179], v[192:195], v[100:103]
	v_mfma_f32_16x16x32_bf16 v[92:95], v[168:171], v[206:209], v[92:95]
	v_mfma_f32_16x16x32_bf16 v[84:87], v[176:179], v[206:209], v[84:87]
	v_mfma_f32_16x16x32_bf16 v[76:79], v[168:171], v[214:217], v[76:79]
	v_mfma_f32_16x16x32_bf16 v[68:71], v[176:179], v[214:217], v[68:71]
	s_setprio 0
	s_barrier
; #define PG8_STAGE(bufoff, gbase, voff) do { _Pragma("unroll") for (int _i = 0; _i < 2; ++_i) \
;         __builtin_amdgcn_global_load_lds((const unsigned*)((const char*)(gbase) + (voff)[_i]), (PG8_LAS unsigned*)(lds + (bufoff) + ldsw + _i * 8192), 16, 0, 0); } while (0)
; #define PG8_LDA(dst, b, h) do { _Pragma("unroll") for (int m = 0; m < 4; ++m) _Pragma("unroll") for (int k = 0; k < 2; ++k) dst[m][k] = *(const PG8_LAS bf16x8*)(lds + PG8_SA(b, h) + aoff + m * 2048 + k * 1024); } while (0)
; #define PG8_MMA(ai, bj, At, Bt) do { __builtin_amdgcn_s_setprio(1); _Pragma("unroll") for (int m = 0; m < 4; ++m) _Pragma("unroll") for (int n = 0; n < 2; ++n) _Pragma("unroll") for (int k = 0; k < 2; ++k) \
;         acc[ai][bj][m][n] = __builtin_amdgcn_mfma_f32_16x16x32_bf16(Bt[n][k], At[m][k], acc[ai][bj][m][n], 0, 0, 0); __builtin_amdgcn_s_setprio(0); } while (0)
; #define PG8_WAIT_V(n) asm volatile("s_waitcnt vmcnt(" #n ")" ::: "memory")
; #define PG8_WAIT_L(n) asm volatile("s_waitcnt lgkmcnt(" #n ")" ::: "memory")
; #define PG8_BAR __builtin_amdgcn_s_barrier()
; #define PG8_SCHED __builtin_amdgcn_sched_barrier(0)
; template <class Epi, class Sched, bool ALIGN_EPI = false, bool SP2 = false>
; __device__ __forceinline__ void gemm_phase(PG8_LAS unsigned char* lds, const Gemm g, const Sched& S, const Epi& E) {
;     ...
;             PG8_LDA(At, 1, 1); PG8_STAGE(PG8_SB(1, 0), b3, voffB); PG8_STAGE(PG8_SB(1, 1), b3 + hstep, voffB); PG8_STAGE(PG8_SA(1, 0), a3, voffA);
;             PG8_WAIT_V(8); PG8_WAIT_L(0); PG8_BAR; PG8_MMA(1, 0, At, B0); PG8_MMA(1, 1, At, B1); PG8_BAR; PG8_SCHED;
;     ...
;         if constexpr (ALIGN_EPI) { if (wr == 0) PG8_BAR; }
	ds_read_b128 v[180:183], v166 offset:49152
	ds_read_b128 v[184:187], v166 offset:50176
	ds_read_b128 v[188:191], v166 offset:51200
	ds_read_b128 v[192:195], v166 offset:52224
	ds_read_b128 v[202:205], v166 offset:53248
	ds_read_b128 v[206:209], v166 offset:54272
	ds_read_b128 v[210:213], v166 offset:55296
	ds_read_b128 v[214:217], v166 offset:56320
	s_add_i32 s26, s47, s35
	s_mov_b32 m0, s26
	v_lshl_add_u64 v[198:199], v[198:199], 0, s[82:83]
	global_load_lds_dwordx4 v[198:199], off
	s_add_i32 m0, s26, 0x2000
	s_add_u32 s24, s24, 0x40080
	v_lshl_add_u64 v[198:199], v[218:219], 0, s[82:83]
	s_addc_u32 s25, s25, 0
	s_add_i32 s26, s48, s35
	global_load_lds_dwordx4 v[198:199], off
	s_mov_b32 m0, s26
	v_lshl_add_u64 v[198:199], s[24:25], 0, v[134:135]
	global_load_lds_dwordx4 v[198:199], off
	s_add_i32 m0, s26, 0x2000
	v_lshl_add_u64 v[198:199], s[24:25], 0, v[0:1]
	global_load_lds_dwordx4 v[198:199], off
	s_mov_b32 m0, s41
	v_lshl_add_u64 v[198:199], v[220:221], 0, s[82:83]
	global_load_lds_dwordx4 v[198:199], off
	s_mov_b32 m0, s42
	v_lshl_add_u64 v[198:199], v[222:223], 0, s[82:83]
	global_load_lds_dwordx4 v[198:199], off
	s_waitcnt vmcnt(8) lgkmcnt(0)
	s_barrier
	s_setprio 1
	v_mfma_f32_16x16x32_bf16 v[64:67], v[144:147], v[180:183], v[64:67]
	v_mfma_f32_16x16x32_bf16 v[56:59], v[152:155], v[180:183], v[56:59]
	v_mfma_f32_16x16x32_bf16 v[48:51], v[144:147], v[188:191], v[48:51]
	v_mfma_f32_16x16x32_bf16 v[40:43], v[152:155], v[188:191], v[40:43]
	v_mfma_f32_16x16x32_bf16 v[32:35], v[144:147], v[202:205], v[32:35]
	v_mfma_f32_16x16x32_bf16 v[24:27], v[152:155], v[202:205], v[24:27]
	v_mfma_f32_16x16x32_bf16 v[16:19], v[144:147], v[210:213], v[16:19]
	v_mfma_f32_16x16x32_bf16 v[8:11], v[152:155], v[210:213], v[8:11]
	v_mfma_f32_16x16x32_bf16 v[64:67], v[148:151], v[184:187], v[64:67]
	v_mfma_f32_16x16x32_bf16 v[56:59], v[156:159], v[184:187], v[56:59]
	v_mfma_f32_16x16x32_bf16 v[48:51], v[148:151], v[192:195], v[48:51]
	v_mfma_f32_16x16x32_bf16 v[40:43], v[156:159], v[192:195], v[40:43]
	v_mfma_f32_16x16x32_bf16 v[32:35], v[148:151], v[206:209], v[32:35]
	v_mfma_f32_16x16x32_bf16 v[24:27], v[156:159], v[206:209], v[24:27]
	v_mfma_f32_16x16x32_bf16 v[16:19], v[148:151], v[214:217], v[16:19]
	v_mfma_f32_16x16x32_bf16 v[8:11], v[156:159], v[214:217], v[8:11]
	s_setprio 0
	s_setprio 1
	v_mfma_f32_16x16x32_bf16 v[60:63], v[160:163], v[180:183], v[60:63]
	v_mfma_f32_16x16x32_bf16 v[52:55], v[172:175], v[180:183], v[52:55]
	v_mfma_f32_16x16x32_bf16 v[44:47], v[160:163], v[188:191], v[44:47]
	v_mfma_f32_16x16x32_bf16 v[36:39], v[172:175], v[188:191], v[36:39]
	v_mfma_f32_16x16x32_bf16 v[28:31], v[160:163], v[202:205], v[28:31]
	v_mfma_f32_16x16x32_bf16 v[20:23], v[172:175], v[202:205], v[20:23]
	v_mfma_f32_16x16x32_bf16 v[12:15], v[160:163], v[210:213], v[12:15]
	v_mfma_f32_16x16x32_bf16 v[4:7], v[172:175], v[210:213], v[4:7]
	v_mfma_f32_16x16x32_bf16 v[60:63], v[168:171], v[184:187], v[60:63]
	v_mfma_f32_16x16x32_bf16 v[52:55], v[176:179], v[184:187], v[52:55]
	v_mfma_f32_16x16x32_bf16 v[44:47], v[168:171], v[192:195], v[44:47]
	v_mfma_f32_16x16x32_bf16 v[36:39], v[176:179], v[192:195], v[36:39]
	v_mfma_f32_16x16x32_bf16 v[28:31], v[168:171], v[206:209], v[28:31]
	v_mfma_f32_16x16x32_bf16 v[20:23], v[176:179], v[206:209], v[20:23]
	v_mfma_f32_16x16x32_bf16 v[12:15], v[168:171], v[214:217], v[12:15]
	v_mfma_f32_16x16x32_bf16 v[4:7], v[176:179], v[214:217], v[4:7]
	s_setprio 0
	s_barrier
	s_add_i32 s46, s46, 2
	s_add_u32 s8, s8, 0x100
	s_addc_u32 s9, s9, 0
	s_add_u32 s44, s44, 0x100
	s_addc_u32 s45, s45, 0
	s_cmp_gt_u32 s46, 13
	s_cbranch_scc0 .LBB0_405
	s_and_b64 vcc, exec, s[14:15]
	s_cbranch_vccz .LBB0_408
	s_barrier

; #define PG8_STAGE(bufoff, gbase, voff) do { _Pragma("unroll") for (int _i = 0; _i < 2; ++_i) \
;         __builtin_amdgcn_global_load_lds((const unsigned*)((const char*)(gbase) + (voff)[_i]), (PG8_LAS unsigned*)(lds + (bufoff) + ldsw + _i * 8192), 16, 0, 0); } while (0)
; #define PG8_LDA(dst, b, h) do { _Pragma("unroll") for (int m = 0; m < 4; ++m) _Pragma("unroll") for (int k = 0; k < 2; ++k) dst[m][k] = *(const PG8_LAS bf16x8*)(lds + PG8_SA(b, h) + aoff + m * 2048 + k * 1024); } while (0)
; #define PG8_LDB(dst, b, h) do { _Pragma("unroll") for (int n = 0; n < 2; ++n) _Pragma("unroll") for (int k = 0; k < 2; ++k) dst[n][k] = *(const PG8_LAS bf16x8*)(lds + PG8_SB(b, h) + boff + n * 2048 + k * 1024); } while (0)
; #define PG8_MMA(ai, bj, At, Bt) do { __builtin_amdgcn_s_setprio(1); _Pragma("unroll") for (int m = 0; m < 4; ++m) _Pragma("unroll") for (int n = 0; n < 2; ++n) _Pragma("unroll") for (int k = 0; k < 2; ++k) \
;         acc[ai][bj][m][n] = __builtin_amdgcn_mfma_f32_16x16x32_bf16(Bt[n][k], At[m][k], acc[ai][bj][m][n], 0, 0, 0); __builtin_amdgcn_s_setprio(0); } while (0)
; #define PG8_WAIT_V(n) asm volatile("s_waitcnt vmcnt(" #n ")" ::: "memory")
; #define PG8_BAR __builtin_amdgcn_s_barrier()
; template <class Epi, class Sched, bool ALIGN_EPI = false, bool SP2 = false>
; __device__ __forceinline__ void gemm_phase(PG8_LAS unsigned char* lds, const Gemm g, const Sched& S, const Epi& E) {
;     ...
;         for (int t = 0; t < nt; t += 2) {
;             const bool last = (t == nt - 2);
;             const char* a1 = cA + (size_t)(t + 1) * kstep;
;             const char* a2 = last ? nA : cA + (size_t)(t + 2) * kstep; const char* b2 = last ? nB : cB + (size_t)(t + 2) * kstep;
;             const char* a3 = a2 + kstep; const char* b3 = b2 + kstep;
;             if (last && has_next) S.a_ready(nxt);
;             if constexpr (SP2) {
;             PG8_LDB(B0, 0, 0); PG8_LDB(B1, 0, 1); PG8_SCHED; PG8_LDA(At, 0, 0); PG8_STAGE(PG8_SA(1, 1), a1 + hstep, voffA);
;             PG8_WAIT_V(8); PG8_WAIT_L(0); PG8_BAR; PG8_MMA(0, 0, At, B0); PG8_MMA(0, 1, At, B1); PG8_BAR; PG8_SCHED;
;             PG8_LDA(At, 0, 1); PG8_STAGE(PG8_SB(0, 0), b2, voffB); PG8_STAGE(PG8_SB(0, 1), b2 + hstep, voffB); PG8_STAGE(PG8_SA(0, 0), a2, voffA);
;             PG8_WAIT_V(8); PG8_WAIT_L(0); PG8_BAR; PG8_MMA(1, 0, At, B0); PG8_MMA(1, 1, At, B1); PG8_BAR; PG8_SCHED;
.LBB0_480:
	ds_read_b128 v[156:159], v236
	ds_read_b128 v[168:171], v236 offset:1024
	ds_read_b128 v[172:175], v236 offset:2048
	ds_read_b128 v[176:179], v236 offset:3072
	ds_read_b128 v[180:183], v236 offset:4096
	ds_read_b128 v[184:187], v236 offset:5120
	ds_read_b128 v[188:191], v236 offset:6144
	ds_read_b128 v[208:211], v236 offset:7168
	v_add_u32_e32 v100, 0x10000, v234
	v_add_u32_e32 v144, 0x14000, v234
	ds_read_b128 v[68:71], v100
	ds_read_b128 v[80:83], v100 offset:1024
	ds_read_b128 v[92:95], v100 offset:2048
	ds_read_b128 v[100:103], v100 offset:3072
	ds_read_b128 v[112:115], v144
	ds_read_b128 v[120:123], v144 offset:1024
	ds_read_b128 v[132:135], v144 offset:2048
	ds_read_b128 v[144:147], v144 offset:3072
	s_add_u32 s8, s26, 0x100
	s_addc_u32 s9, s27, 0
	s_add_i32 s54, 0, 0x10000
	s_cmp_eq_u32 s53, 40
	s_cselect_b32 s31, s23, s9
	s_cselect_b32 s30, s22, s8
	s_cselect_b32 s29, s25, s45
	s_cselect_b32 s28, s24, s44
	s_add_i32 s55, 0, 0x14000
	s_add_i32 m0, s40, 0xc000
	v_lshl_add_u64 v[198:199], s[26:27], 0, v[204:205]
	global_load_lds_dwordx4 v[198:199], off
	s_add_i32 m0, s40, 0xe000
	v_lshl_add_u64 v[198:199], s[26:27], 0, v[206:207]
	global_load_lds_dwordx4 v[198:199], off
	s_waitcnt vmcnt(8) lgkmcnt(0)
	s_barrier
	s_setprio 1
	v_mfma_f32_16x16x32_bf16 v[164:167], v[68:71], v[156:159], v[164:167]
	v_mfma_f32_16x16x32_bf16 v[160:163], v[92:95], v[156:159], v[160:163]
	v_mfma_f32_16x16x32_bf16 v[140:143], v[68:71], v[172:175], v[140:143]
	v_mfma_f32_16x16x32_bf16 v[136:139], v[92:95], v[172:175], v[136:139]
	v_mfma_f32_16x16x32_bf16 v[116:119], v[68:71], v[180:183], v[116:119]
	v_mfma_f32_16x16x32_bf16 v[108:111], v[92:95], v[180:183], v[108:111]
	v_mfma_f32_16x16x32_bf16 v[88:91], v[68:71], v[188:191], v[88:91]
	v_mfma_f32_16x16x32_bf16 v[84:87], v[92:95], v[188:191], v[84:87]
	v_mfma_f32_16x16x32_bf16 v[164:167], v[80:83], v[168:171], v[164:167]
	v_mfma_f32_16x16x32_bf16 v[160:163], v[100:103], v[168:171], v[160:163]
	v_mfma_f32_16x16x32_bf16 v[140:143], v[80:83], v[176:179], v[140:143]
	v_mfma_f32_16x16x32_bf16 v[136:139], v[100:103], v[176:179], v[136:139]
	v_mfma_f32_16x16x32_bf16 v[116:119], v[80:83], v[184:187], v[116:119]
	v_mfma_f32_16x16x32_bf16 v[108:111], v[100:103], v[184:187], v[108:111]
	v_mfma_f32_16x16x32_bf16 v[88:91], v[80:83], v[208:211], v[88:91]
	v_mfma_f32_16x16x32_bf16 v[84:87], v[100:103], v[208:211], v[84:87]
	s_setprio 0
	s_setprio 1
	v_mfma_f32_16x16x32_bf16 v[152:155], v[112:115], v[156:159], v[152:155]
	v_mfma_f32_16x16x32_bf16 v[148:151], v[132:135], v[156:159], v[148:151]
	v_mfma_f32_16x16x32_bf16 v[128:131], v[112:115], v[172:175], v[128:131]
	v_mfma_f32_16x16x32_bf16 v[124:127], v[132:135], v[172:175], v[124:127]
	v_mfma_f32_16x16x32_bf16 v[104:107], v[112:115], v[180:183], v[104:107]
	v_mfma_f32_16x16x32_bf16 v[96:99], v[132:135], v[180:183], v[96:99]
	v_mfma_f32_16x16x32_bf16 v[76:79], v[112:115], v[188:191], v[76:79]
	v_mfma_f32_16x16x32_bf16 v[72:75], v[132:135], v[188:191], v[72:75]
	v_mfma_f32_16x16x32_bf16 v[152:155], v[120:123], v[168:171], v[152:155]
	v_mfma_f32_16x16x32_bf16 v[148:151], v[144:147], v[168:171], v[148:151]
	v_mfma_f32_16x16x32_bf16 v[128:131], v[120:123], v[176:179], v[128:131]
	v_mfma_f32_16x16x32_bf16 v[124:127], v[144:147], v[176:179], v[124:127]
	v_mfma_f32_16x16x32_bf16 v[104:107], v[120:123], v[184:187], v[104:107]
	v_mfma_f32_16x16x32_bf16 v[96:99], v[144:147], v[184:187], v[96:99]
	v_mfma_f32_16x16x32_bf16 v[76:79], v[120:123], v[208:211], v[76:79]
	v_mfma_f32_16x16x32_bf16 v[72:75], v[144:147], v[208:211], v[72:75]
	s_setprio 0
	s_barrier
	ds_read_b128 v[156:159], v236 offset:16384
	ds_read_b128 v[168:171], v236 offset:17408
	ds_read_b128 v[172:175], v236 offset:18432
	ds_read_b128 v[176:179], v236 offset:19456
	ds_read_b128 v[180:183], v236 offset:20480
	ds_read_b128 v[184:187], v236 offset:21504
	ds_read_b128 v[188:191], v236 offset:22528
	ds_read_b128 v[208:211], v236 offset:23552
	s_add_i32 s26, s54, s39
	s_mov_b32 m0, s26
	v_lshl_add_u64 v[198:199], s[28:29], 0, v[192:193]
	global_load_lds_dwordx4 v[198:199], off
	s_add_i32 m0, s26, 0x2000
	s_add_u32 s26, s28, 0xb0000
	v_lshl_add_u64 v[212:213], s[28:29], 0, v[202:203]
	s_addc_u32 s27, s29, 0
	s_add_i32 s54, s55, s39
	global_load_lds_dwordx4 v[212:213], off
	v_lshl_add_u64 v[214:215], s[26:27], 0, v[192:193]
	s_mov_b32 m0, s54
	v_lshl_add_u64 v[216:217], s[30:31], 0, v[194:195]
	global_load_lds_dwordx4 v[214:215], off
	s_add_i32 m0, s54, 0x2000
	v_lshl_add_u64 v[214:215], s[26:27], 0, v[202:203]
	global_load_lds_dwordx4 v[214:215], off
	s_mov_b32 m0, s40
	v_lshl_add_u64 v[214:215], s[30:31], 0, v[0:1]
	global_load_lds_dwordx4 v[214:215], off
	s_mov_b32 m0, s41
	s_add_i32 s54, 0, 0x18000
	global_load_lds_dwordx4 v[216:217], off
	s_waitcnt vmcnt(8) lgkmcnt(0)
	s_barrier
; #define PG8_STAGE(bufoff, gbase, voff) do { _Pragma("unroll") for (int _i = 0; _i < 2; ++_i) \
;         __builtin_amdgcn_global_load_lds((const unsigned*)((const char*)(gbase) + (voff)[_i]), (PG8_LAS unsigned*)(lds + (bufoff) + ldsw + _i * 8192), 16, 0, 0); } while (0)
; #define PG8_LDA(dst, b, h) do { _Pragma("unroll") for (int m = 0; m < 4; ++m) _Pragma("unroll") for (int k = 0; k < 2; ++k) dst[m][k] = *(const PG8_LAS bf16x8*)(lds + PG8_SA(b, h) + aoff + m * 2048 + k * 1024); } while (0)
; #define PG8_LDB(dst, b, h) do { _Pragma("unroll") for (int n = 0; n < 2; ++n) _Pragma("unroll") for (int k = 0; k < 2; ++k) dst[n][k] = *(const PG8_LAS bf16x8*)(lds + PG8_SB(b, h) + boff + n * 2048 + k * 1024); } while (0)
; #define PG8_MMA(ai, bj, At, Bt) do { __builtin_amdgcn_s_setprio(1); _Pragma("unroll") for (int m = 0; m < 4; ++m) _Pragma("unroll") for (int n = 0; n < 2; ++n) _Pragma("unroll") for (int k = 0; k < 2; ++k) \
;         acc[ai][bj][m][n] = __builtin_amdgcn_mfma_f32_16x16x32_bf16(Bt[n][k], At[m][k], acc[ai][bj][m][n], 0, 0, 0); __builtin_amdgcn_s_setprio(0); } while (0)
; #define PG8_WAIT_V(n) asm volatile("s_waitcnt vmcnt(" #n ")" ::: "memory")
; #define PG8_WAIT_L(n) asm volatile("s_waitcnt lgkmcnt(" #n ")" ::: "memory")
; #define PG8_BAR __builtin_amdgcn_s_barrier()
; #define PG8_SCHED __builtin_amdgcn_sched_barrier(0)
; template <class Epi, class Sched, bool ALIGN_EPI = false, bool SP2 = false>
; __device__ __forceinline__ void gemm_phase(PG8_LAS unsigned char* lds, const Gemm g, const Sched& S, const Epi& E) {
;     ...
;             PG8_WAIT_V(8); PG8_WAIT_L(0); PG8_BAR; PG8_MMA(1, 0, At, B0); PG8_MMA(1, 1, At, B1); PG8_BAR; PG8_SCHED;
;             PG8_LDB(B0, 1, 0); PG8_LDB(B1, 1, 1); PG8_SCHED; PG8_LDA(At, 1, 0); PG8_STAGE(PG8_SA(0, 1), a2 + hstep, voffA);
;             PG8_WAIT_V(8); PG8_WAIT_L(0); PG8_BAR; PG8_MMA(0, 0, At, B0); PG8_MMA(0, 1, At, B1); PG8_BAR; PG8_SCHED;
	s_setprio 1
	v_mfma_f32_16x16x32_bf16 v[64:67], v[68:71], v[156:159], v[64:67]
	v_mfma_f32_16x16x32_bf16 v[60:63], v[92:95], v[156:159], v[60:63]
	v_mfma_f32_16x16x32_bf16 v[48:51], v[68:71], v[172:175], v[48:51]
	v_mfma_f32_16x16x32_bf16 v[44:47], v[92:95], v[172:175], v[44:47]
	v_mfma_f32_16x16x32_bf16 v[32:35], v[68:71], v[180:183], v[32:35]
	v_mfma_f32_16x16x32_bf16 v[28:31], v[92:95], v[180:183], v[28:31]
	v_mfma_f32_16x16x32_bf16 v[16:19], v[68:71], v[188:191], v[16:19]
	v_mfma_f32_16x16x32_bf16 v[12:15], v[92:95], v[188:191], v[12:15]
	v_mfma_f32_16x16x32_bf16 v[64:67], v[80:83], v[168:171], v[64:67]
	v_mfma_f32_16x16x32_bf16 v[60:63], v[100:103], v[168:171], v[60:63]
	v_mfma_f32_16x16x32_bf16 v[48:51], v[80:83], v[176:179], v[48:51]
	v_mfma_f32_16x16x32_bf16 v[44:47], v[100:103], v[176:179], v[44:47]
	v_mfma_f32_16x16x32_bf16 v[32:35], v[80:83], v[184:187], v[32:35]
	v_mfma_f32_16x16x32_bf16 v[28:31], v[100:103], v[184:187], v[28:31]
	v_mfma_f32_16x16x32_bf16 v[16:19], v[80:83], v[208:211], v[16:19]
	v_mfma_f32_16x16x32_bf16 v[12:15], v[100:103], v[208:211], v[12:15]
	s_setprio 0
	s_setprio 1
	v_mfma_f32_16x16x32_bf16 v[56:59], v[112:115], v[156:159], v[56:59]
	v_mfma_f32_16x16x32_bf16 v[52:55], v[132:135], v[156:159], v[52:55]
	v_mfma_f32_16x16x32_bf16 v[40:43], v[112:115], v[172:175], v[40:43]
	v_mfma_f32_16x16x32_bf16 v[36:39], v[132:135], v[172:175], v[36:39]
	v_mfma_f32_16x16x32_bf16 v[24:27], v[112:115], v[180:183], v[24:27]
	v_mfma_f32_16x16x32_bf16 v[20:23], v[132:135], v[180:183], v[20:23]
	v_mfma_f32_16x16x32_bf16 v[8:11], v[112:115], v[188:191], v[8:11]
	v_mfma_f32_16x16x32_bf16 v[4:7], v[132:135], v[188:191], v[4:7]
	v_mfma_f32_16x16x32_bf16 v[56:59], v[120:123], v[168:171], v[56:59]
	v_mfma_f32_16x16x32_bf16 v[52:55], v[144:147], v[168:171], v[52:55]
	v_mfma_f32_16x16x32_bf16 v[40:43], v[120:123], v[176:179], v[40:43]
	v_mfma_f32_16x16x32_bf16 v[36:39], v[144:147], v[176:179], v[36:39]
	v_mfma_f32_16x16x32_bf16 v[24:27], v[120:123], v[184:187], v[24:27]
	v_mfma_f32_16x16x32_bf16 v[20:23], v[144:147], v[184:187], v[20:23]
	v_mfma_f32_16x16x32_bf16 v[8:11], v[120:123], v[208:211], v[8:11]
	v_mfma_f32_16x16x32_bf16 v[4:7], v[144:147], v[208:211], v[4:7]
	s_setprio 0
	s_barrier
	ds_read_b128 v[156:159], v236 offset:32768
	ds_read_b128 v[168:171], v236 offset:33792
	ds_read_b128 v[172:175], v236 offset:34816
	ds_read_b128 v[176:179], v236 offset:35840
	ds_read_b128 v[180:183], v236 offset:36864
	ds_read_b128 v[184:187], v236 offset:37888
	ds_read_b128 v[188:191], v236 offset:38912
	ds_read_b128 v[208:211], v236 offset:39936
	v_add_u32_e32 v100, 0x18000, v234
	v_add_u32_e32 v144, 0x1c000, v234
	ds_read_b128 v[68:71], v100
	ds_read_b128 v[80:83], v100 offset:1024
	ds_read_b128 v[92:95], v100 offset:2048
	ds_read_b128 v[100:103], v100 offset:3072
	ds_read_b128 v[112:115], v144
	ds_read_b128 v[120:123], v144 offset:1024
	ds_read_b128 v[132:135], v144 offset:2048
	ds_read_b128 v[144:147], v144 offset:3072
	s_add_i32 s55, 0, 0x1c000
	s_add_u32 s26, s30, 0xb0000
	s_addc_u32 s27, s31, 0
	s_mov_b32 m0, s42
	v_lshl_add_u64 v[218:219], s[26:27], 0, v[0:1]
	global_load_lds_dwordx4 v[218:219], off
	s_mov_b32 m0, s43
	v_lshl_add_u64 v[218:219], s[26:27], 0, v[194:195]
	global_load_lds_dwordx4 v[218:219], off
	s_waitcnt vmcnt(8) lgkmcnt(0)
	s_barrier
	s_setprio 1
	v_mfma_f32_16x16x32_bf16 v[164:167], v[68:71], v[156:159], v[164:167]
	v_mfma_f32_16x16x32_bf16 v[160:163], v[92:95], v[156:159], v[160:163]
	v_mfma_f32_16x16x32_bf16 v[140:143], v[68:71], v[172:175], v[140:143]
	v_mfma_f32_16x16x32_bf16 v[136:139], v[92:95], v[172:175], v[136:139]
	v_mfma_f32_16x16x32_bf16 v[116:119], v[68:71], v[180:183], v[116:119]
	v_mfma_f32_16x16x32_bf16 v[108:111], v[92:95], v[180:183], v[108:111]
	v_mfma_f32_16x16x32_bf16 v[88:91], v[68:71], v[188:191], v[88:91]
	v_mfma_f32_16x16x32_bf16 v[84:87], v[92:95], v[188:191], v[84:87]
	v_mfma_f32_16x16x32_bf16 v[164:167], v[80:83], v[168:171], v[164:167]
	v_mfma_f32_16x16x32_bf16 v[160:163], v[100:103], v[168:171], v[160:163]
	v_mfma_f32_16x16x32_bf16 v[140:143], v[80:83], v[176:179], v[140:143]
	v_mfma_f32_16x16x32_bf16 v[136:139], v[100:103], v[176:179], v[136:139]
	v_mfma_f32_16x16x32_bf16 v[116:119], v[80:83], v[184:187], v[116:119]
	v_mfma_f32_16x16x32_bf16 v[108:111], v[100:103], v[184:187], v[108:111]
	v_mfma_f32_16x16x32_bf16 v[88:91], v[80:83], v[208:211], v[88:91]
	v_mfma_f32_16x16x32_bf16 v[84:87], v[100:103], v[208:211], v[84:87]
	s_setprio 0
	s_setprio 1
	v_mfma_f32_16x16x32_bf16 v[152:155], v[112:115], v[156:159], v[152:155]
	v_mfma_f32_16x16x32_bf16 v[148:151], v[132:135], v[156:159], v[148:151]
	v_mfma_f32_16x16x32_bf16 v[128:131], v[112:115], v[172:175], v[128:131]
	v_mfma_f32_16x16x32_bf16 v[124:127], v[132:135], v[172:175], v[124:127]
	v_mfma_f32_16x16x32_bf16 v[104:107], v[112:115], v[180:183], v[104:107]
	v_mfma_f32_16x16x32_bf16 v[96:99], v[132:135], v[180:183], v[96:99]
	v_mfma_f32_16x16x32_bf16 v[76:79], v[112:115], v[188:191], v[76:79]
	v_mfma_f32_16x16x32_bf16 v[72:75], v[132:135], v[188:191], v[72:75]
	v_mfma_f32_16x16x32_bf16 v[152:155], v[120:123], v[168:171], v[152:155]
	v_mfma_f32_16x16x32_bf16 v[148:151], v[144:147], v[168:171], v[148:151]
	v_mfma_f32_16x16x32_bf16 v[128:131], v[120:123], v[176:179], v[128:131]
	v_mfma_f32_16x16x32_bf16 v[124:127], v[144:147], v[176:179], v[124:127]
	v_mfma_f32_16x16x32_bf16 v[104:107], v[120:123], v[184:187], v[104:107]
	v_mfma_f32_16x16x32_bf16 v[96:99], v[144:147], v[184:187], v[96:99]
	v_mfma_f32_16x16x32_bf16 v[76:79], v[120:123], v[208:211], v[76:79]
	v_mfma_f32_16x16x32_bf16 v[72:75], v[144:147], v[208:211], v[72:75]
	s_setprio 0
	s_barrier
; #define PG8_STAGE(bufoff, gbase, voff) do { _Pragma("unroll") for (int _i = 0; _i < 2; ++_i) \
;         __builtin_amdgcn_global_load_lds((const unsigned*)((const char*)(gbase) + (voff)[_i]), (PG8_LAS unsigned*)(lds + (bufoff) + ldsw + _i * 8192), 16, 0, 0); } while (0)
; #define PG8_LDA(dst, b, h) do { _Pragma("unroll") for (int m = 0; m < 4; ++m) _Pragma("unroll") for (int k = 0; k < 2; ++k) dst[m][k] = *(const PG8_LAS bf16x8*)(lds + PG8_SA(b, h) + aoff + m * 2048 + k * 1024); } while (0)
; #define PG8_MMA(ai, bj, At, Bt) do { __builtin_amdgcn_s_setprio(1); _Pragma("unroll") for (int m = 0; m < 4; ++m) _Pragma("unroll") for (int n = 0; n < 2; ++n) _Pragma("unroll") for (int k = 0; k < 2; ++k) \
;         acc[ai][bj][m][n] = __builtin_amdgcn_mfma_f32_16x16x32_bf16(Bt[n][k], At[m][k], acc[ai][bj][m][n], 0, 0, 0); __builtin_amdgcn_s_setprio(0); } while (0)
; #define PG8_WAIT_V(n) asm volatile("s_waitcnt vmcnt(" #n ")" ::: "memory")
; #define PG8_WAIT_L(n) asm volatile("s_waitcnt lgkmcnt(" #n ")" ::: "memory")
; #define PG8_BAR __builtin_amdgcn_s_barrier()
; #define PG8_SCHED __builtin_amdgcn_sched_barrier(0)
; template <class Epi, class Sched, bool ALIGN_EPI = false, bool SP2 = false>
; __device__ __forceinline__ void gemm_phase(PG8_LAS unsigned char* lds, const Gemm g, const Sched& S, const Epi& E) {
;     ...
;             PG8_LDA(At, 1, 1); PG8_STAGE(PG8_SB(1, 0), b3, voffB); PG8_STAGE(PG8_SB(1, 1), b3 + hstep, voffB); PG8_STAGE(PG8_SA(1, 0), a3, voffA);
;             PG8_WAIT_V(8); PG8_WAIT_L(0); PG8_BAR; PG8_MMA(1, 0, At, B0); PG8_MMA(1, 1, At, B1); PG8_BAR; PG8_SCHED;
;     ...
;         if constexpr (ALIGN_EPI) { if (wr == 0) PG8_BAR; }
	ds_read_b128 v[156:159], v236 offset:49152
	ds_read_b128 v[168:171], v236 offset:50176
	ds_read_b128 v[172:175], v236 offset:51200
	ds_read_b128 v[176:179], v236 offset:52224
	ds_read_b128 v[180:183], v236 offset:53248
	ds_read_b128 v[184:187], v236 offset:54272
	ds_read_b128 v[188:191], v236 offset:55296
	ds_read_b128 v[208:211], v236 offset:56320
	s_add_i32 s26, s54, s39
	s_mov_b32 m0, s26
	v_lshl_add_u64 v[198:199], v[198:199], 0, s[82:83]
	global_load_lds_dwordx4 v[198:199], off
	s_add_i32 m0, s26, 0x2000
	s_add_u32 s26, s28, 0xb0080
	v_lshl_add_u64 v[198:199], v[212:213], 0, s[82:83]
	s_addc_u32 s27, s29, 0
	s_add_i32 s28, s55, s39
	global_load_lds_dwordx4 v[198:199], off
	s_mov_b32 m0, s28
	v_lshl_add_u64 v[198:199], s[26:27], 0, v[192:193]
	global_load_lds_dwordx4 v[198:199], off
	s_add_i32 m0, s28, 0x2000
	v_lshl_add_u64 v[198:199], s[26:27], 0, v[202:203]
	global_load_lds_dwordx4 v[198:199], off
	s_mov_b32 m0, s47
	v_lshl_add_u64 v[198:199], v[214:215], 0, s[82:83]
	global_load_lds_dwordx4 v[198:199], off
	s_mov_b32 m0, s48
	v_lshl_add_u64 v[198:199], v[216:217], 0, s[82:83]
	global_load_lds_dwordx4 v[198:199], off
	s_waitcnt vmcnt(8) lgkmcnt(0)
	s_barrier
	s_setprio 1
	v_mfma_f32_16x16x32_bf16 v[64:67], v[68:71], v[156:159], v[64:67]
	v_mfma_f32_16x16x32_bf16 v[60:63], v[92:95], v[156:159], v[60:63]
	v_mfma_f32_16x16x32_bf16 v[48:51], v[68:71], v[172:175], v[48:51]
	v_mfma_f32_16x16x32_bf16 v[44:47], v[92:95], v[172:175], v[44:47]
	v_mfma_f32_16x16x32_bf16 v[32:35], v[68:71], v[180:183], v[32:35]
	v_mfma_f32_16x16x32_bf16 v[28:31], v[92:95], v[180:183], v[28:31]
	v_mfma_f32_16x16x32_bf16 v[16:19], v[68:71], v[188:191], v[16:19]
	v_mfma_f32_16x16x32_bf16 v[12:15], v[92:95], v[188:191], v[12:15]
	v_mfma_f32_16x16x32_bf16 v[64:67], v[80:83], v[168:171], v[64:67]
	v_mfma_f32_16x16x32_bf16 v[60:63], v[100:103], v[168:171], v[60:63]
	v_mfma_f32_16x16x32_bf16 v[48:51], v[80:83], v[176:179], v[48:51]
	v_mfma_f32_16x16x32_bf16 v[44:47], v[100:103], v[176:179], v[44:47]
	v_mfma_f32_16x16x32_bf16 v[32:35], v[80:83], v[184:187], v[32:35]
	v_mfma_f32_16x16x32_bf16 v[28:31], v[100:103], v[184:187], v[28:31]
	v_mfma_f32_16x16x32_bf16 v[16:19], v[80:83], v[208:211], v[16:19]
	v_mfma_f32_16x16x32_bf16 v[12:15], v[100:103], v[208:211], v[12:15]
	s_setprio 0
	s_setprio 1
	v_mfma_f32_16x16x32_bf16 v[56:59], v[112:115], v[156:159], v[56:59]
	v_mfma_f32_16x16x32_bf16 v[52:55], v[132:135], v[156:159], v[52:55]
	v_mfma_f32_16x16x32_bf16 v[40:43], v[112:115], v[172:175], v[40:43]
	v_mfma_f32_16x16x32_bf16 v[36:39], v[132:135], v[172:175], v[36:39]
	v_mfma_f32_16x16x32_bf16 v[24:27], v[112:115], v[180:183], v[24:27]
	v_mfma_f32_16x16x32_bf16 v[20:23], v[132:135], v[180:183], v[20:23]
	v_mfma_f32_16x16x32_bf16 v[8:11], v[112:115], v[188:191], v[8:11]
	v_mfma_f32_16x16x32_bf16 v[4:7], v[132:135], v[188:191], v[4:7]
	v_mfma_f32_16x16x32_bf16 v[56:59], v[120:123], v[168:171], v[56:59]
	v_mfma_f32_16x16x32_bf16 v[52:55], v[144:147], v[168:171], v[52:55]
	v_mfma_f32_16x16x32_bf16 v[40:43], v[120:123], v[176:179], v[40:43]
	v_mfma_f32_16x16x32_bf16 v[36:39], v[144:147], v[176:179], v[36:39]
	v_mfma_f32_16x16x32_bf16 v[24:27], v[120:123], v[184:187], v[24:27]
	v_mfma_f32_16x16x32_bf16 v[20:23], v[144:147], v[184:187], v[20:23]
	v_mfma_f32_16x16x32_bf16 v[8:11], v[120:123], v[208:211], v[8:11]
	v_mfma_f32_16x16x32_bf16 v[4:7], v[144:147], v[208:211], v[4:7]
	s_setprio 0
	s_barrier
	s_add_i32 s53, s53, 2
	s_add_u32 s44, s44, 0x100
	s_addc_u32 s45, s45, 0
	s_cmp_gt_u32 s53, 41
	s_mov_b64 s[26:27], s[8:9]
	s_cbranch_scc0 .LBB0_480
	s_and_b64 vcc, exec, s[20:21]
	s_cbranch_vccz .LBB0_483
	s_barrier
